# pool_mix fully hand-written (all four window classes), next load set issued ahead of the current set's stores; replaces the compiled pool loop when grid is 256
# baseline (speedup 1.0000x reference)
.Lmix_pool:
	s_mul_i32 s14, s13, 0x18000
	s_add_i32 s6, s6, s14
	s_add_i32 s99, s14, 0x257fff
	s_mov_b32 s101, 6
	v_readlane_b32 s38, v252, 45
	v_readlane_b32 s39, v252, 46
	v_add_u32_e32 v25, s6, v241
	s_mov_b32 s47, 0xaaab
	s_add_u32 s10, s38, 0xd800000
	s_addc_u32 s11, s39, 0
	s_add_u32 s12, s38, 0x9800000
	s_addc_u32 s13, s39, 0
	s_mov_b32 s44, 0
	s_mov_b32 s46, 0x0
	v_add_u32_e32 v144, s46, v25
	v_lshrrev_b32_e32 v145, 6, v144
	v_mul_u32_u24_e32 v145, s47, v145
	v_lshrrev_b32_e32 v145, 17, v145
	v_mul_u32_u24_e32 v146, 0xc0, v145
	v_sub_u32_e32 v146, v144, v146
	v_lshrrev_b32_e32 v147, 3, v146
	v_mul_u32_u24_e32 v147, s47, v147
	v_lshrrev_b32_e32 v147, 17, v147
	v_mul_u32_u24_e32 v24, 24, v147
	v_sub_u32_e32 v24, v146, v24
	v_lshl_add_u32 v145, v145, 3, v147
	v_and_b32_e32 v6, 0x1fff, v145
	v_lshlrev_b32_e32 v145, 11, v145
	v_lshl_add_u32 v0, v24, 4, v145
	s_mov_b32 s46, 0x4000
	v_add_u32_e32 v144, s46, v25
	v_lshrrev_b32_e32 v145, 6, v144
	v_mul_u32_u24_e32 v145, s47, v145
	v_lshrrev_b32_e32 v145, 17, v145
	v_mul_u32_u24_e32 v146, 0xc0, v145
	v_sub_u32_e32 v146, v144, v146
	v_lshrrev_b32_e32 v147, 3, v146
	v_mul_u32_u24_e32 v147, s47, v147
	v_lshrrev_b32_e32 v147, 17, v147
	v_mul_u32_u24_e32 v24, 24, v147
	v_sub_u32_e32 v24, v146, v24
	v_lshl_add_u32 v145, v145, 3, v147
	v_and_b32_e32 v7, 0x1fff, v145
	v_lshlrev_b32_e32 v145, 11, v145
	v_lshl_add_u32 v1, v24, 4, v145
	s_mov_b32 s46, 0x8000
	v_add_u32_e32 v144, s46, v25
	v_lshrrev_b32_e32 v145, 6, v144
	v_mul_u32_u24_e32 v145, s47, v145
	v_lshrrev_b32_e32 v145, 17, v145
	v_mul_u32_u24_e32 v146, 0xc0, v145
	v_sub_u32_e32 v146, v144, v146
	v_lshrrev_b32_e32 v147, 3, v146
	v_mul_u32_u24_e32 v147, s47, v147
	v_lshrrev_b32_e32 v147, 17, v147
	v_mul_u32_u24_e32 v24, 24, v147
	v_sub_u32_e32 v24, v146, v24
	v_lshl_add_u32 v145, v145, 3, v147
	v_and_b32_e32 v8, 0x1fff, v145
	v_lshlrev_b32_e32 v145, 11, v145
	v_lshl_add_u32 v2, v24, 4, v145
	s_mov_b32 s46, 0xc000
	v_add_u32_e32 v144, s46, v25
	v_lshrrev_b32_e32 v145, 6, v144
	v_mul_u32_u24_e32 v145, s47, v145
	v_lshrrev_b32_e32 v145, 17, v145
	v_mul_u32_u24_e32 v146, 0xc0, v145
	v_sub_u32_e32 v146, v144, v146
	v_lshrrev_b32_e32 v147, 3, v146
	v_mul_u32_u24_e32 v147, s47, v147
	v_lshrrev_b32_e32 v147, 17, v147
	v_mul_u32_u24_e32 v24, 24, v147
	v_sub_u32_e32 v24, v146, v24
	v_lshl_add_u32 v145, v145, 3, v147
	v_and_b32_e32 v9, 0x1fff, v145
	v_lshlrev_b32_e32 v145, 11, v145
	v_lshl_add_u32 v3, v24, 4, v145
	s_mov_b32 s46, 0x10000
	v_add_u32_e32 v144, s46, v25
	v_lshrrev_b32_e32 v145, 6, v144
	v_mul_u32_u24_e32 v145, s47, v145
	v_lshrrev_b32_e32 v145, 17, v145
	v_mul_u32_u24_e32 v146, 0xc0, v145
	v_sub_u32_e32 v146, v144, v146
	v_lshrrev_b32_e32 v147, 3, v146
	v_mul_u32_u24_e32 v147, s47, v147
	v_lshrrev_b32_e32 v147, 17, v147
	v_mul_u32_u24_e32 v24, 24, v147
	v_sub_u32_e32 v24, v146, v24
	v_lshl_add_u32 v145, v145, 3, v147
	v_and_b32_e32 v10, 0x1fff, v145
	v_lshlrev_b32_e32 v145, 11, v145
	v_lshl_add_u32 v4, v24, 4, v145
	s_mov_b32 s46, 0x14000
	v_add_u32_e32 v144, s46, v25
	v_lshrrev_b32_e32 v145, 6, v144
	v_mul_u32_u24_e32 v145, s47, v145
	v_lshrrev_b32_e32 v145, 17, v145
	v_mul_u32_u24_e32 v146, 0xc0, v145
	v_sub_u32_e32 v146, v144, v146
	v_lshrrev_b32_e32 v147, 3, v146
	v_mul_u32_u24_e32 v147, s47, v147
	v_lshrrev_b32_e32 v147, 17, v147
	v_mul_u32_u24_e32 v24, 24, v147
	v_sub_u32_e32 v24, v146, v24
	v_lshl_add_u32 v145, v145, 3, v147
	v_and_b32_e32 v11, 0x1fff, v145
	v_lshlrev_b32_e32 v145, 11, v145
	v_lshl_add_u32 v5, v24, 4, v145
	global_load_dwordx4 v[28:31], v0, s[10:11]
	v_min_u32_e32 v26, 1, v6
	v_lshlrev_b32_e32 v26, 11, v26
	v_sub_u32_e32 v26, v0, v26
	global_load_dwordx4 v[32:35], v26, s[10:11]
	global_load_dwordx4 v[36:39], v1, s[10:11]
	v_min_u32_e32 v26, 1, v7
	v_lshlrev_b32_e32 v26, 11, v26
	v_sub_u32_e32 v26, v1, v26
	global_load_dwordx4 v[40:43], v26, s[10:11]
	global_load_dwordx4 v[44:47], v2, s[10:11]
	v_min_u32_e32 v26, 1, v8
	v_lshlrev_b32_e32 v26, 11, v26
	v_sub_u32_e32 v26, v2, v26
	global_load_dwordx4 v[48:51], v26, s[10:11]
	global_load_dwordx4 v[52:55], v3, s[10:11]
	v_min_u32_e32 v26, 1, v9
	v_lshlrev_b32_e32 v26, 11, v26
	v_sub_u32_e32 v26, v3, v26
	global_load_dwordx4 v[56:59], v26, s[10:11]
	global_load_dwordx4 v[60:63], v4, s[10:11]
	v_min_u32_e32 v26, 1, v10
	v_lshlrev_b32_e32 v26, 11, v26
	v_sub_u32_e32 v26, v4, v26
	global_load_dwordx4 v[64:67], v26, s[10:11]
	global_load_dwordx4 v[68:71], v5, s[10:11]
	v_min_u32_e32 v26, 1, v11
	v_lshlrev_b32_e32 v26, 11, v26
	v_sub_u32_e32 v26, v5, v26
	global_load_dwordx4 v[72:75], v26, s[10:11]
	s_waitcnt vmcnt(0)
	v_lshlrev_b32_e32 v116, 16, v28
	v_and_b32_e32 v117, 0xffff0000, v28
	v_lshlrev_b32_e32 v118, 16, v29
	v_and_b32_e32 v119, 0xffff0000, v29
	v_lshlrev_b32_e32 v120, 16, v30
	v_and_b32_e32 v121, 0xffff0000, v30
	v_lshlrev_b32_e32 v122, 16, v31
	v_and_b32_e32 v123, 0xffff0000, v31
	v_cmp_le_u32_e32 vcc, 1, v6
	v_cndmask_b32_e64 v140, 0, 1.0, vcc
	v_mov_b32_e32 v141, v140
	v_lshlrev_b32_e32 v132, 16, v32
	v_and_b32_e32 v133, 0xffff0000, v32
	v_lshlrev_b32_e32 v134, 16, v33
	v_and_b32_e32 v135, 0xffff0000, v33
	v_lshlrev_b32_e32 v136, 16, v34
	v_and_b32_e32 v137, 0xffff0000, v34
	v_lshlrev_b32_e32 v138, 16, v35
	v_and_b32_e32 v139, 0xffff0000, v35
	v_pk_fma_f32 v[124:125], v[132:133], v[140:141], v[116:117]
	v_pk_fma_f32 v[126:127], v[134:135], v[140:141], v[118:119]
	v_pk_fma_f32 v[128:129], v[136:137], v[140:141], v[120:121]
	v_pk_fma_f32 v[130:131], v[138:139], v[140:141], v[122:123]
	v_add_u32_e32 v144, 1, v6
	v_min_u32_e32 v144, 2, v144
	v_cvt_f32_u32_e32 v144, v144
	v_rcp_f32_e32 v142, v144
	s_nop 0
	v_fma_f32 v145, -v144, v142, 1.0
	v_fma_f32 v142, v145, v142, v142
	v_mov_b32_e32 v143, v142
	v_pk_fma_f32 v[132:133], v[124:125], v[142:143], v[116:117] neg_lo:[0,0,1] neg_hi:[0,0,1]
	v_pk_fma_f32 v[134:135], v[126:127], v[142:143], v[118:119] neg_lo:[0,0,1] neg_hi:[0,0,1]
	v_pk_fma_f32 v[136:137], v[128:129], v[142:143], v[120:121] neg_lo:[0,0,1] neg_hi:[0,0,1]
	v_pk_fma_f32 v[138:139], v[130:131], v[142:143], v[122:123] neg_lo:[0,0,1] neg_hi:[0,0,1]
	v_cvt_pk_bf16_f32 v92, v132, v133
	v_cvt_pk_bf16_f32 v93, v134, v135
	v_cvt_pk_bf16_f32 v94, v136, v137
	v_cvt_pk_bf16_f32 v95, v138, v139
	v_lshlrev_b32_e32 v116, 16, v36
	v_and_b32_e32 v117, 0xffff0000, v36
	v_lshlrev_b32_e32 v118, 16, v37
	v_and_b32_e32 v119, 0xffff0000, v37
	v_lshlrev_b32_e32 v120, 16, v38
	v_and_b32_e32 v121, 0xffff0000, v38
	v_lshlrev_b32_e32 v122, 16, v39
	v_and_b32_e32 v123, 0xffff0000, v39
	v_cmp_le_u32_e32 vcc, 1, v7
	v_cndmask_b32_e64 v140, 0, 1.0, vcc
	v_mov_b32_e32 v141, v140
	v_lshlrev_b32_e32 v132, 16, v40
	v_and_b32_e32 v133, 0xffff0000, v40
	v_lshlrev_b32_e32 v134, 16, v41
	v_and_b32_e32 v135, 0xffff0000, v41
	v_lshlrev_b32_e32 v136, 16, v42
	v_and_b32_e32 v137, 0xffff0000, v42
	v_lshlrev_b32_e32 v138, 16, v43
	v_and_b32_e32 v139, 0xffff0000, v43
	v_pk_fma_f32 v[124:125], v[132:133], v[140:141], v[116:117]
	v_pk_fma_f32 v[126:127], v[134:135], v[140:141], v[118:119]
	v_pk_fma_f32 v[128:129], v[136:137], v[140:141], v[120:121]
	v_pk_fma_f32 v[130:131], v[138:139], v[140:141], v[122:123]
	v_add_u32_e32 v144, 1, v7
	v_min_u32_e32 v144, 2, v144
	v_cvt_f32_u32_e32 v144, v144
	v_rcp_f32_e32 v142, v144
	s_nop 0
	v_fma_f32 v145, -v144, v142, 1.0
	v_fma_f32 v142, v145, v142, v142
	v_mov_b32_e32 v143, v142
	v_pk_fma_f32 v[132:133], v[124:125], v[142:143], v[116:117] neg_lo:[0,0,1] neg_hi:[0,0,1]
	v_pk_fma_f32 v[134:135], v[126:127], v[142:143], v[118:119] neg_lo:[0,0,1] neg_hi:[0,0,1]
	v_pk_fma_f32 v[136:137], v[128:129], v[142:143], v[120:121] neg_lo:[0,0,1] neg_hi:[0,0,1]
	v_pk_fma_f32 v[138:139], v[130:131], v[142:143], v[122:123] neg_lo:[0,0,1] neg_hi:[0,0,1]
	v_cvt_pk_bf16_f32 v96, v132, v133
	v_cvt_pk_bf16_f32 v97, v134, v135
	v_cvt_pk_bf16_f32 v98, v136, v137
	v_cvt_pk_bf16_f32 v99, v138, v139
	v_lshlrev_b32_e32 v116, 16, v44
	v_and_b32_e32 v117, 0xffff0000, v44
	v_lshlrev_b32_e32 v118, 16, v45
	v_and_b32_e32 v119, 0xffff0000, v45
	v_lshlrev_b32_e32 v120, 16, v46
	v_and_b32_e32 v121, 0xffff0000, v46
	v_lshlrev_b32_e32 v122, 16, v47
	v_and_b32_e32 v123, 0xffff0000, v47
	v_cmp_le_u32_e32 vcc, 1, v8
	v_cndmask_b32_e64 v140, 0, 1.0, vcc
	v_mov_b32_e32 v141, v140
	v_lshlrev_b32_e32 v132, 16, v48
	v_and_b32_e32 v133, 0xffff0000, v48
	v_lshlrev_b32_e32 v134, 16, v49
	v_and_b32_e32 v135, 0xffff0000, v49
	v_lshlrev_b32_e32 v136, 16, v50
	v_and_b32_e32 v137, 0xffff0000, v50
	v_lshlrev_b32_e32 v138, 16, v51
	v_and_b32_e32 v139, 0xffff0000, v51
	v_pk_fma_f32 v[124:125], v[132:133], v[140:141], v[116:117]
	v_pk_fma_f32 v[126:127], v[134:135], v[140:141], v[118:119]
	v_pk_fma_f32 v[128:129], v[136:137], v[140:141], v[120:121]
	v_pk_fma_f32 v[130:131], v[138:139], v[140:141], v[122:123]
	v_add_u32_e32 v144, 1, v8
	v_min_u32_e32 v144, 2, v144
	v_cvt_f32_u32_e32 v144, v144
	v_rcp_f32_e32 v142, v144
	s_nop 0
	v_fma_f32 v145, -v144, v142, 1.0
	v_fma_f32 v142, v145, v142, v142
	v_mov_b32_e32 v143, v142
	v_pk_fma_f32 v[132:133], v[124:125], v[142:143], v[116:117] neg_lo:[0,0,1] neg_hi:[0,0,1]
	v_pk_fma_f32 v[134:135], v[126:127], v[142:143], v[118:119] neg_lo:[0,0,1] neg_hi:[0,0,1]
	v_pk_fma_f32 v[136:137], v[128:129], v[142:143], v[120:121] neg_lo:[0,0,1] neg_hi:[0,0,1]
	v_pk_fma_f32 v[138:139], v[130:131], v[142:143], v[122:123] neg_lo:[0,0,1] neg_hi:[0,0,1]
	v_cvt_pk_bf16_f32 v100, v132, v133
	v_cvt_pk_bf16_f32 v101, v134, v135
	v_cvt_pk_bf16_f32 v102, v136, v137
	v_cvt_pk_bf16_f32 v103, v138, v139
	v_lshlrev_b32_e32 v116, 16, v52
	v_and_b32_e32 v117, 0xffff0000, v52
	v_lshlrev_b32_e32 v118, 16, v53
	v_and_b32_e32 v119, 0xffff0000, v53
	v_lshlrev_b32_e32 v120, 16, v54
	v_and_b32_e32 v121, 0xffff0000, v54
	v_lshlrev_b32_e32 v122, 16, v55
	v_and_b32_e32 v123, 0xffff0000, v55
	v_cmp_le_u32_e32 vcc, 1, v9
	v_cndmask_b32_e64 v140, 0, 1.0, vcc
	v_mov_b32_e32 v141, v140
	v_lshlrev_b32_e32 v132, 16, v56
	v_and_b32_e32 v133, 0xffff0000, v56
	v_lshlrev_b32_e32 v134, 16, v57
	v_and_b32_e32 v135, 0xffff0000, v57
	v_lshlrev_b32_e32 v136, 16, v58
	v_and_b32_e32 v137, 0xffff0000, v58
	v_lshlrev_b32_e32 v138, 16, v59
	v_and_b32_e32 v139, 0xffff0000, v59
	v_pk_fma_f32 v[124:125], v[132:133], v[140:141], v[116:117]
	v_pk_fma_f32 v[126:127], v[134:135], v[140:141], v[118:119]
	v_pk_fma_f32 v[128:129], v[136:137], v[140:141], v[120:121]
	v_pk_fma_f32 v[130:131], v[138:139], v[140:141], v[122:123]
	v_add_u32_e32 v144, 1, v9
	v_min_u32_e32 v144, 2, v144
	v_cvt_f32_u32_e32 v144, v144
	v_rcp_f32_e32 v142, v144
	s_nop 0
	v_fma_f32 v145, -v144, v142, 1.0
	v_fma_f32 v142, v145, v142, v142
	v_mov_b32_e32 v143, v142
	v_pk_fma_f32 v[132:133], v[124:125], v[142:143], v[116:117] neg_lo:[0,0,1] neg_hi:[0,0,1]
	v_pk_fma_f32 v[134:135], v[126:127], v[142:143], v[118:119] neg_lo:[0,0,1] neg_hi:[0,0,1]
	v_pk_fma_f32 v[136:137], v[128:129], v[142:143], v[120:121] neg_lo:[0,0,1] neg_hi:[0,0,1]
	v_pk_fma_f32 v[138:139], v[130:131], v[142:143], v[122:123] neg_lo:[0,0,1] neg_hi:[0,0,1]
	v_cvt_pk_bf16_f32 v104, v132, v133
	v_cvt_pk_bf16_f32 v105, v134, v135
	v_cvt_pk_bf16_f32 v106, v136, v137
	v_cvt_pk_bf16_f32 v107, v138, v139
	v_lshlrev_b32_e32 v116, 16, v60
	v_and_b32_e32 v117, 0xffff0000, v60
	v_lshlrev_b32_e32 v118, 16, v61
	v_and_b32_e32 v119, 0xffff0000, v61
	v_lshlrev_b32_e32 v120, 16, v62
	v_and_b32_e32 v121, 0xffff0000, v62
	v_lshlrev_b32_e32 v122, 16, v63
	v_and_b32_e32 v123, 0xffff0000, v63
	v_cmp_le_u32_e32 vcc, 1, v10
	v_cndmask_b32_e64 v140, 0, 1.0, vcc
	v_mov_b32_e32 v141, v140
	v_lshlrev_b32_e32 v132, 16, v64
	v_and_b32_e32 v133, 0xffff0000, v64
	v_lshlrev_b32_e32 v134, 16, v65
	v_and_b32_e32 v135, 0xffff0000, v65
	v_lshlrev_b32_e32 v136, 16, v66
	v_and_b32_e32 v137, 0xffff0000, v66
	v_lshlrev_b32_e32 v138, 16, v67
	v_and_b32_e32 v139, 0xffff0000, v67
	v_pk_fma_f32 v[124:125], v[132:133], v[140:141], v[116:117]
	v_pk_fma_f32 v[126:127], v[134:135], v[140:141], v[118:119]
	v_pk_fma_f32 v[128:129], v[136:137], v[140:141], v[120:121]
	v_pk_fma_f32 v[130:131], v[138:139], v[140:141], v[122:123]
	v_add_u32_e32 v144, 1, v10
	v_min_u32_e32 v144, 2, v144
	v_cvt_f32_u32_e32 v144, v144
	v_rcp_f32_e32 v142, v144
	s_nop 0
	v_fma_f32 v145, -v144, v142, 1.0
	v_fma_f32 v142, v145, v142, v142
	v_mov_b32_e32 v143, v142
	v_pk_fma_f32 v[132:133], v[124:125], v[142:143], v[116:117] neg_lo:[0,0,1] neg_hi:[0,0,1]
	v_pk_fma_f32 v[134:135], v[126:127], v[142:143], v[118:119] neg_lo:[0,0,1] neg_hi:[0,0,1]
	v_pk_fma_f32 v[136:137], v[128:129], v[142:143], v[120:121] neg_lo:[0,0,1] neg_hi:[0,0,1]
	v_pk_fma_f32 v[138:139], v[130:131], v[142:143], v[122:123] neg_lo:[0,0,1] neg_hi:[0,0,1]
	v_cvt_pk_bf16_f32 v108, v132, v133
	v_cvt_pk_bf16_f32 v109, v134, v135
	v_cvt_pk_bf16_f32 v110, v136, v137
	v_cvt_pk_bf16_f32 v111, v138, v139
	v_lshlrev_b32_e32 v116, 16, v68
	v_and_b32_e32 v117, 0xffff0000, v68
	v_lshlrev_b32_e32 v118, 16, v69
	v_and_b32_e32 v119, 0xffff0000, v69
	v_lshlrev_b32_e32 v120, 16, v70
	v_and_b32_e32 v121, 0xffff0000, v70
	v_lshlrev_b32_e32 v122, 16, v71
	v_and_b32_e32 v123, 0xffff0000, v71
	v_cmp_le_u32_e32 vcc, 1, v11
	v_cndmask_b32_e64 v140, 0, 1.0, vcc
	v_mov_b32_e32 v141, v140
	v_lshlrev_b32_e32 v132, 16, v72
	v_and_b32_e32 v133, 0xffff0000, v72
	v_lshlrev_b32_e32 v134, 16, v73
	v_and_b32_e32 v135, 0xffff0000, v73
	v_lshlrev_b32_e32 v136, 16, v74
	v_and_b32_e32 v137, 0xffff0000, v74
	v_lshlrev_b32_e32 v138, 16, v75
	v_and_b32_e32 v139, 0xffff0000, v75
	v_pk_fma_f32 v[124:125], v[132:133], v[140:141], v[116:117]
	v_pk_fma_f32 v[126:127], v[134:135], v[140:141], v[118:119]
	v_pk_fma_f32 v[128:129], v[136:137], v[140:141], v[120:121]
	v_pk_fma_f32 v[130:131], v[138:139], v[140:141], v[122:123]
	v_add_u32_e32 v144, 1, v11
	v_min_u32_e32 v144, 2, v144
	v_cvt_f32_u32_e32 v144, v144
	v_rcp_f32_e32 v142, v144
	s_nop 0
	v_fma_f32 v145, -v144, v142, 1.0
	v_fma_f32 v142, v145, v142, v142
	v_mov_b32_e32 v143, v142
	v_pk_fma_f32 v[132:133], v[124:125], v[142:143], v[116:117] neg_lo:[0,0,1] neg_hi:[0,0,1]
	v_pk_fma_f32 v[134:135], v[126:127], v[142:143], v[118:119] neg_lo:[0,0,1] neg_hi:[0,0,1]
	v_pk_fma_f32 v[136:137], v[128:129], v[142:143], v[120:121] neg_lo:[0,0,1] neg_hi:[0,0,1]
	v_pk_fma_f32 v[138:139], v[130:131], v[142:143], v[122:123] neg_lo:[0,0,1] neg_hi:[0,0,1]
	v_cvt_pk_bf16_f32 v112, v132, v133
	v_cvt_pk_bf16_f32 v113, v134, v135
	v_cvt_pk_bf16_f32 v114, v136, v137
	v_cvt_pk_bf16_f32 v115, v138, v139
	global_store_dwordx4 v0, v[92:95], s[12:13]
	global_store_dwordx4 v1, v[96:99], s[12:13]
	global_store_dwordx4 v2, v[100:103], s[12:13]
	global_store_dwordx4 v3, v[104:107], s[12:13]
	global_store_dwordx4 v4, v[108:111], s[12:13]
	global_store_dwordx4 v5, v[112:115], s[12:13]
	s_mov_b32 s44, 0
	s_mov_b32 s46, 0x0
	v_add_u32_e32 v144, s46, v25
	v_lshrrev_b32_e32 v145, 6, v144
	v_mul_u32_u24_e32 v145, s47, v145
	v_lshrrev_b32_e32 v145, 17, v145
	v_mul_u32_u24_e32 v146, 0xc0, v145
	v_sub_u32_e32 v146, v144, v146
	v_lshrrev_b32_e32 v147, 3, v146
	v_mul_u32_u24_e32 v147, s47, v147
	v_lshrrev_b32_e32 v147, 17, v147
	v_mul_u32_u24_e32 v24, 24, v147
	v_sub_u32_e32 v24, v146, v24
	v_lshl_add_u32 v145, v145, 3, v147
	v_and_b32_e32 v6, 0x1fff, v145
	v_lshlrev_b32_e32 v145, 11, v145
	v_lshl_add_u32 v0, v24, 4, v145
	s_mov_b32 s46, 0x4000
	v_add_u32_e32 v144, s46, v25
	v_lshrrev_b32_e32 v145, 6, v144
	v_mul_u32_u24_e32 v145, s47, v145
	v_lshrrev_b32_e32 v145, 17, v145
	v_mul_u32_u24_e32 v146, 0xc0, v145
	v_sub_u32_e32 v146, v144, v146
	v_lshrrev_b32_e32 v147, 3, v146
	v_mul_u32_u24_e32 v147, s47, v147
	v_lshrrev_b32_e32 v147, 17, v147
	v_mul_u32_u24_e32 v24, 24, v147
	v_sub_u32_e32 v24, v146, v24
	v_lshl_add_u32 v145, v145, 3, v147
	v_and_b32_e32 v7, 0x1fff, v145
	v_lshlrev_b32_e32 v145, 11, v145
	v_lshl_add_u32 v1, v24, 4, v145
	s_mov_b32 s46, 0x8000
	v_add_u32_e32 v144, s46, v25
	v_lshrrev_b32_e32 v145, 6, v144
	v_mul_u32_u24_e32 v145, s47, v145
	v_lshrrev_b32_e32 v145, 17, v145
	v_mul_u32_u24_e32 v146, 0xc0, v145
	v_sub_u32_e32 v146, v144, v146
	v_lshrrev_b32_e32 v147, 3, v146
	v_mul_u32_u24_e32 v147, s47, v147
	v_lshrrev_b32_e32 v147, 17, v147
	v_mul_u32_u24_e32 v24, 24, v147
	v_sub_u32_e32 v24, v146, v24
	v_lshl_add_u32 v145, v145, 3, v147
	v_and_b32_e32 v8, 0x1fff, v145
	v_lshlrev_b32_e32 v145, 11, v145
	v_lshl_add_u32 v2, v24, 4, v145
	global_load_dwordx4 v[28:31], v0, s[10:11] offset:384
	v_min_u32_e32 v26, 1, v6
	v_lshlrev_b32_e32 v26, 11, v26
	v_sub_u32_e32 v26, v0, v26
	global_load_dwordx4 v[32:35], v26, s[10:11] offset:384
	v_min_u32_e32 v26, 2, v6
	v_lshlrev_b32_e32 v26, 11, v26
	v_sub_u32_e32 v26, v0, v26
	global_load_dwordx4 v[36:39], v26, s[10:11] offset:384
	v_min_u32_e32 v26, 3, v6
	v_lshlrev_b32_e32 v26, 11, v26
	v_sub_u32_e32 v26, v0, v26
	global_load_dwordx4 v[40:43], v26, s[10:11] offset:384
	global_load_dwordx4 v[44:47], v1, s[10:11] offset:384
	v_min_u32_e32 v26, 1, v7
	v_lshlrev_b32_e32 v26, 11, v26
	v_sub_u32_e32 v26, v1, v26
	global_load_dwordx4 v[48:51], v26, s[10:11] offset:384
	v_min_u32_e32 v26, 2, v7
	v_lshlrev_b32_e32 v26, 11, v26
	v_sub_u32_e32 v26, v1, v26
	global_load_dwordx4 v[52:55], v26, s[10:11] offset:384
	v_min_u32_e32 v26, 3, v7
	v_lshlrev_b32_e32 v26, 11, v26
	v_sub_u32_e32 v26, v1, v26
	global_load_dwordx4 v[56:59], v26, s[10:11] offset:384
	global_load_dwordx4 v[60:63], v2, s[10:11] offset:384
	v_min_u32_e32 v26, 1, v8
	v_lshlrev_b32_e32 v26, 11, v26
	v_sub_u32_e32 v26, v2, v26
	global_load_dwordx4 v[64:67], v26, s[10:11] offset:384
	v_min_u32_e32 v26, 2, v8
	v_lshlrev_b32_e32 v26, 11, v26
	v_sub_u32_e32 v26, v2, v26
	global_load_dwordx4 v[68:71], v26, s[10:11] offset:384
	v_min_u32_e32 v26, 3, v8
	v_lshlrev_b32_e32 v26, 11, v26
	v_sub_u32_e32 v26, v2, v26
	global_load_dwordx4 v[72:75], v26, s[10:11] offset:384
	s_waitcnt vmcnt(0)
.Lpool_c1:
	v_lshlrev_b32_e32 v116, 16, v28
	v_and_b32_e32 v117, 0xffff0000, v28
	v_lshlrev_b32_e32 v118, 16, v29
	v_and_b32_e32 v119, 0xffff0000, v29
	v_lshlrev_b32_e32 v120, 16, v30
	v_and_b32_e32 v121, 0xffff0000, v30
	v_lshlrev_b32_e32 v122, 16, v31
	v_and_b32_e32 v123, 0xffff0000, v31
	v_cmp_le_u32_e32 vcc, 1, v6
	v_cndmask_b32_e64 v140, 0, 1.0, vcc
	v_mov_b32_e32 v141, v140
	v_lshlrev_b32_e32 v132, 16, v32
	v_and_b32_e32 v133, 0xffff0000, v32
	v_lshlrev_b32_e32 v134, 16, v33
	v_and_b32_e32 v135, 0xffff0000, v33
	v_lshlrev_b32_e32 v136, 16, v34
	v_and_b32_e32 v137, 0xffff0000, v34
	v_lshlrev_b32_e32 v138, 16, v35
	v_and_b32_e32 v139, 0xffff0000, v35
	v_pk_fma_f32 v[124:125], v[132:133], v[140:141], v[116:117]
	v_pk_fma_f32 v[126:127], v[134:135], v[140:141], v[118:119]
	v_pk_fma_f32 v[128:129], v[136:137], v[140:141], v[120:121]
	v_pk_fma_f32 v[130:131], v[138:139], v[140:141], v[122:123]
	v_cmp_le_u32_e32 vcc, 2, v6
	v_cndmask_b32_e64 v140, 0, 1.0, vcc
	v_mov_b32_e32 v141, v140
	v_lshlrev_b32_e32 v132, 16, v36
	v_and_b32_e32 v133, 0xffff0000, v36
	v_lshlrev_b32_e32 v134, 16, v37
	v_and_b32_e32 v135, 0xffff0000, v37
	v_lshlrev_b32_e32 v136, 16, v38
	v_and_b32_e32 v137, 0xffff0000, v38
	v_lshlrev_b32_e32 v138, 16, v39
	v_and_b32_e32 v139, 0xffff0000, v39
	v_pk_fma_f32 v[124:125], v[132:133], v[140:141], v[124:125]
	v_pk_fma_f32 v[126:127], v[134:135], v[140:141], v[126:127]
	v_pk_fma_f32 v[128:129], v[136:137], v[140:141], v[128:129]
	v_pk_fma_f32 v[130:131], v[138:139], v[140:141], v[130:131]
	v_cmp_le_u32_e32 vcc, 3, v6
	v_cndmask_b32_e64 v140, 0, 1.0, vcc
	v_mov_b32_e32 v141, v140
	v_lshlrev_b32_e32 v132, 16, v40
	v_and_b32_e32 v133, 0xffff0000, v40
	v_lshlrev_b32_e32 v134, 16, v41
	v_and_b32_e32 v135, 0xffff0000, v41
	v_lshlrev_b32_e32 v136, 16, v42
	v_and_b32_e32 v137, 0xffff0000, v42
	v_lshlrev_b32_e32 v138, 16, v43
	v_and_b32_e32 v139, 0xffff0000, v43
	v_pk_fma_f32 v[124:125], v[132:133], v[140:141], v[124:125]
	v_pk_fma_f32 v[126:127], v[134:135], v[140:141], v[126:127]
	v_pk_fma_f32 v[128:129], v[136:137], v[140:141], v[128:129]
	v_pk_fma_f32 v[130:131], v[138:139], v[140:141], v[130:131]
	v_add_u32_e32 v144, 1, v6
	v_min_u32_e32 v144, 4, v144
	v_cvt_f32_u32_e32 v144, v144
	v_rcp_f32_e32 v142, v144
	s_nop 0
	v_fma_f32 v145, -v144, v142, 1.0
	v_fma_f32 v142, v145, v142, v142
	v_mov_b32_e32 v143, v142
	v_pk_fma_f32 v[132:133], v[124:125], v[142:143], v[116:117] neg_lo:[0,0,1] neg_hi:[0,0,1]
	v_pk_fma_f32 v[134:135], v[126:127], v[142:143], v[118:119] neg_lo:[0,0,1] neg_hi:[0,0,1]
	v_pk_fma_f32 v[136:137], v[128:129], v[142:143], v[120:121] neg_lo:[0,0,1] neg_hi:[0,0,1]
	v_pk_fma_f32 v[138:139], v[130:131], v[142:143], v[122:123] neg_lo:[0,0,1] neg_hi:[0,0,1]
	v_cvt_pk_bf16_f32 v92, v132, v133
	v_cvt_pk_bf16_f32 v93, v134, v135
	v_cvt_pk_bf16_f32 v94, v136, v137
	v_cvt_pk_bf16_f32 v95, v138, v139
	v_lshlrev_b32_e32 v116, 16, v44
	v_and_b32_e32 v117, 0xffff0000, v44
	v_lshlrev_b32_e32 v118, 16, v45
	v_and_b32_e32 v119, 0xffff0000, v45
	v_lshlrev_b32_e32 v120, 16, v46
	v_and_b32_e32 v121, 0xffff0000, v46
	v_lshlrev_b32_e32 v122, 16, v47
	v_and_b32_e32 v123, 0xffff0000, v47
	v_cmp_le_u32_e32 vcc, 1, v7
	v_cndmask_b32_e64 v140, 0, 1.0, vcc
	v_mov_b32_e32 v141, v140
	v_lshlrev_b32_e32 v132, 16, v48
	v_and_b32_e32 v133, 0xffff0000, v48
	v_lshlrev_b32_e32 v134, 16, v49
	v_and_b32_e32 v135, 0xffff0000, v49
	v_lshlrev_b32_e32 v136, 16, v50
	v_and_b32_e32 v137, 0xffff0000, v50
	v_lshlrev_b32_e32 v138, 16, v51
	v_and_b32_e32 v139, 0xffff0000, v51
	v_pk_fma_f32 v[124:125], v[132:133], v[140:141], v[116:117]
	v_pk_fma_f32 v[126:127], v[134:135], v[140:141], v[118:119]
	v_pk_fma_f32 v[128:129], v[136:137], v[140:141], v[120:121]
	v_pk_fma_f32 v[130:131], v[138:139], v[140:141], v[122:123]
	v_cmp_le_u32_e32 vcc, 2, v7
	v_cndmask_b32_e64 v140, 0, 1.0, vcc
	v_mov_b32_e32 v141, v140
	v_lshlrev_b32_e32 v132, 16, v52
	v_and_b32_e32 v133, 0xffff0000, v52
	v_lshlrev_b32_e32 v134, 16, v53
	v_and_b32_e32 v135, 0xffff0000, v53
	v_lshlrev_b32_e32 v136, 16, v54
	v_and_b32_e32 v137, 0xffff0000, v54
	v_lshlrev_b32_e32 v138, 16, v55
	v_and_b32_e32 v139, 0xffff0000, v55
	v_pk_fma_f32 v[124:125], v[132:133], v[140:141], v[124:125]
	v_pk_fma_f32 v[126:127], v[134:135], v[140:141], v[126:127]
	v_pk_fma_f32 v[128:129], v[136:137], v[140:141], v[128:129]
	v_pk_fma_f32 v[130:131], v[138:139], v[140:141], v[130:131]
	v_cmp_le_u32_e32 vcc, 3, v7
	v_cndmask_b32_e64 v140, 0, 1.0, vcc
	v_mov_b32_e32 v141, v140
	v_lshlrev_b32_e32 v132, 16, v56
	v_and_b32_e32 v133, 0xffff0000, v56
	v_lshlrev_b32_e32 v134, 16, v57
	v_and_b32_e32 v135, 0xffff0000, v57
	v_lshlrev_b32_e32 v136, 16, v58
	v_and_b32_e32 v137, 0xffff0000, v58
	v_lshlrev_b32_e32 v138, 16, v59
	v_and_b32_e32 v139, 0xffff0000, v59
	v_pk_fma_f32 v[124:125], v[132:133], v[140:141], v[124:125]
	v_pk_fma_f32 v[126:127], v[134:135], v[140:141], v[126:127]
	v_pk_fma_f32 v[128:129], v[136:137], v[140:141], v[128:129]
	v_pk_fma_f32 v[130:131], v[138:139], v[140:141], v[130:131]
	v_add_u32_e32 v144, 1, v7
	v_min_u32_e32 v144, 4, v144
	v_cvt_f32_u32_e32 v144, v144
	v_rcp_f32_e32 v142, v144
	s_nop 0
	v_fma_f32 v145, -v144, v142, 1.0
	v_fma_f32 v142, v145, v142, v142
	v_mov_b32_e32 v143, v142
	v_pk_fma_f32 v[132:133], v[124:125], v[142:143], v[116:117] neg_lo:[0,0,1] neg_hi:[0,0,1]
	v_pk_fma_f32 v[134:135], v[126:127], v[142:143], v[118:119] neg_lo:[0,0,1] neg_hi:[0,0,1]
	v_pk_fma_f32 v[136:137], v[128:129], v[142:143], v[120:121] neg_lo:[0,0,1] neg_hi:[0,0,1]
	v_pk_fma_f32 v[138:139], v[130:131], v[142:143], v[122:123] neg_lo:[0,0,1] neg_hi:[0,0,1]
	v_cvt_pk_bf16_f32 v96, v132, v133
	v_cvt_pk_bf16_f32 v97, v134, v135
	v_cvt_pk_bf16_f32 v98, v136, v137
	v_cvt_pk_bf16_f32 v99, v138, v139
	v_lshlrev_b32_e32 v116, 16, v60
	v_and_b32_e32 v117, 0xffff0000, v60
	v_lshlrev_b32_e32 v118, 16, v61
	v_and_b32_e32 v119, 0xffff0000, v61
	v_lshlrev_b32_e32 v120, 16, v62
	v_and_b32_e32 v121, 0xffff0000, v62
	v_lshlrev_b32_e32 v122, 16, v63
	v_and_b32_e32 v123, 0xffff0000, v63
	v_cmp_le_u32_e32 vcc, 1, v8
	v_cndmask_b32_e64 v140, 0, 1.0, vcc
	v_mov_b32_e32 v141, v140
	v_lshlrev_b32_e32 v132, 16, v64
	v_and_b32_e32 v133, 0xffff0000, v64
	v_lshlrev_b32_e32 v134, 16, v65
	v_and_b32_e32 v135, 0xffff0000, v65
	v_lshlrev_b32_e32 v136, 16, v66
	v_and_b32_e32 v137, 0xffff0000, v66
	v_lshlrev_b32_e32 v138, 16, v67
	v_and_b32_e32 v139, 0xffff0000, v67
	v_pk_fma_f32 v[124:125], v[132:133], v[140:141], v[116:117]
	v_pk_fma_f32 v[126:127], v[134:135], v[140:141], v[118:119]
	v_pk_fma_f32 v[128:129], v[136:137], v[140:141], v[120:121]
	v_pk_fma_f32 v[130:131], v[138:139], v[140:141], v[122:123]
	v_cmp_le_u32_e32 vcc, 2, v8
	v_cndmask_b32_e64 v140, 0, 1.0, vcc
	v_mov_b32_e32 v141, v140
	v_lshlrev_b32_e32 v132, 16, v68
	v_and_b32_e32 v133, 0xffff0000, v68
	v_lshlrev_b32_e32 v134, 16, v69
	v_and_b32_e32 v135, 0xffff0000, v69
	v_lshlrev_b32_e32 v136, 16, v70
	v_and_b32_e32 v137, 0xffff0000, v70
	v_lshlrev_b32_e32 v138, 16, v71
	v_and_b32_e32 v139, 0xffff0000, v71
	v_pk_fma_f32 v[124:125], v[132:133], v[140:141], v[124:125]
	v_pk_fma_f32 v[126:127], v[134:135], v[140:141], v[126:127]
	v_pk_fma_f32 v[128:129], v[136:137], v[140:141], v[128:129]
	v_pk_fma_f32 v[130:131], v[138:139], v[140:141], v[130:131]
	v_cmp_le_u32_e32 vcc, 3, v8
	v_cndmask_b32_e64 v140, 0, 1.0, vcc
	v_mov_b32_e32 v141, v140
	v_lshlrev_b32_e32 v132, 16, v72
	v_and_b32_e32 v133, 0xffff0000, v72
	v_lshlrev_b32_e32 v134, 16, v73
	v_and_b32_e32 v135, 0xffff0000, v73
	v_lshlrev_b32_e32 v136, 16, v74
	v_and_b32_e32 v137, 0xffff0000, v74
	v_lshlrev_b32_e32 v138, 16, v75
	v_and_b32_e32 v139, 0xffff0000, v75
	v_pk_fma_f32 v[124:125], v[132:133], v[140:141], v[124:125]
	v_pk_fma_f32 v[126:127], v[134:135], v[140:141], v[126:127]
	v_pk_fma_f32 v[128:129], v[136:137], v[140:141], v[128:129]
	v_pk_fma_f32 v[130:131], v[138:139], v[140:141], v[130:131]
	v_add_u32_e32 v144, 1, v8
	v_min_u32_e32 v144, 4, v144
	v_cvt_f32_u32_e32 v144, v144
	v_rcp_f32_e32 v142, v144
	s_nop 0
	v_fma_f32 v145, -v144, v142, 1.0
	v_fma_f32 v142, v145, v142, v142
	v_mov_b32_e32 v143, v142
	v_pk_fma_f32 v[132:133], v[124:125], v[142:143], v[116:117] neg_lo:[0,0,1] neg_hi:[0,0,1]
	v_pk_fma_f32 v[134:135], v[126:127], v[142:143], v[118:119] neg_lo:[0,0,1] neg_hi:[0,0,1]
	v_pk_fma_f32 v[136:137], v[128:129], v[142:143], v[120:121] neg_lo:[0,0,1] neg_hi:[0,0,1]
	v_pk_fma_f32 v[138:139], v[130:131], v[142:143], v[122:123] neg_lo:[0,0,1] neg_hi:[0,0,1]
	v_cvt_pk_bf16_f32 v100, v132, v133
	v_cvt_pk_bf16_f32 v101, v134, v135
	v_cvt_pk_bf16_f32 v102, v136, v137
	v_cvt_pk_bf16_f32 v103, v138, v139
	s_add_i32 s44, s44, 1
	s_cmp_lt_u32 s44, 2
	s_cbranch_scc0 .Lpool_c1_last
	s_mul_i32 s45, s44, 3
	s_add_i32 s46, s45, 0
	s_lshl_b32 s46, s46, 14
	v_add_u32_e32 v144, s46, v25
	v_lshrrev_b32_e32 v145, 6, v144
	v_mul_u32_u24_e32 v145, s47, v145
	v_lshrrev_b32_e32 v145, 17, v145
	v_mul_u32_u24_e32 v146, 0xc0, v145
	v_sub_u32_e32 v146, v144, v146
	v_lshrrev_b32_e32 v147, 3, v146
	v_mul_u32_u24_e32 v147, s47, v147
	v_lshrrev_b32_e32 v147, 17, v147
	v_mul_u32_u24_e32 v24, 24, v147
	v_sub_u32_e32 v24, v146, v24
	v_lshl_add_u32 v145, v145, 3, v147
	v_and_b32_e32 v18, 0x1fff, v145
	v_lshlrev_b32_e32 v145, 11, v145
	v_lshl_add_u32 v12, v24, 4, v145
	s_add_i32 s46, s45, 1
	s_lshl_b32 s46, s46, 14
	v_add_u32_e32 v144, s46, v25
	v_lshrrev_b32_e32 v145, 6, v144
	v_mul_u32_u24_e32 v145, s47, v145
	v_lshrrev_b32_e32 v145, 17, v145
	v_mul_u32_u24_e32 v146, 0xc0, v145
	v_sub_u32_e32 v146, v144, v146
	v_lshrrev_b32_e32 v147, 3, v146
	v_mul_u32_u24_e32 v147, s47, v147
	v_lshrrev_b32_e32 v147, 17, v147
	v_mul_u32_u24_e32 v24, 24, v147
	v_sub_u32_e32 v24, v146, v24
	v_lshl_add_u32 v145, v145, 3, v147
	v_and_b32_e32 v19, 0x1fff, v145
	v_lshlrev_b32_e32 v145, 11, v145
	v_lshl_add_u32 v13, v24, 4, v145
	s_add_i32 s46, s45, 2
	s_lshl_b32 s46, s46, 14
	v_add_u32_e32 v144, s46, v25
	v_lshrrev_b32_e32 v145, 6, v144
	v_mul_u32_u24_e32 v145, s47, v145
	v_lshrrev_b32_e32 v145, 17, v145
	v_mul_u32_u24_e32 v146, 0xc0, v145
	v_sub_u32_e32 v146, v144, v146
	v_lshrrev_b32_e32 v147, 3, v146
	v_mul_u32_u24_e32 v147, s47, v147
	v_lshrrev_b32_e32 v147, 17, v147
	v_mul_u32_u24_e32 v24, 24, v147
	v_sub_u32_e32 v24, v146, v24
	v_lshl_add_u32 v145, v145, 3, v147
	v_and_b32_e32 v20, 0x1fff, v145
	v_lshlrev_b32_e32 v145, 11, v145
	v_lshl_add_u32 v14, v24, 4, v145
	global_load_dwordx4 v[28:31], v12, s[10:11] offset:384
	v_min_u32_e32 v26, 1, v18
	v_lshlrev_b32_e32 v26, 11, v26
	v_sub_u32_e32 v26, v12, v26
	global_load_dwordx4 v[32:35], v26, s[10:11] offset:384
	v_min_u32_e32 v26, 2, v18
	v_lshlrev_b32_e32 v26, 11, v26
	v_sub_u32_e32 v26, v12, v26
	global_load_dwordx4 v[36:39], v26, s[10:11] offset:384
	v_min_u32_e32 v26, 3, v18
	v_lshlrev_b32_e32 v26, 11, v26
	v_sub_u32_e32 v26, v12, v26
	global_load_dwordx4 v[40:43], v26, s[10:11] offset:384
	global_load_dwordx4 v[44:47], v13, s[10:11] offset:384
	v_min_u32_e32 v26, 1, v19
	v_lshlrev_b32_e32 v26, 11, v26
	v_sub_u32_e32 v26, v13, v26
	global_load_dwordx4 v[48:51], v26, s[10:11] offset:384
	v_min_u32_e32 v26, 2, v19
	v_lshlrev_b32_e32 v26, 11, v26
	v_sub_u32_e32 v26, v13, v26
	global_load_dwordx4 v[52:55], v26, s[10:11] offset:384
	v_min_u32_e32 v26, 3, v19
	v_lshlrev_b32_e32 v26, 11, v26
	v_sub_u32_e32 v26, v13, v26
	global_load_dwordx4 v[56:59], v26, s[10:11] offset:384
	global_load_dwordx4 v[60:63], v14, s[10:11] offset:384
	v_min_u32_e32 v26, 1, v20
	v_lshlrev_b32_e32 v26, 11, v26
	v_sub_u32_e32 v26, v14, v26
	global_load_dwordx4 v[64:67], v26, s[10:11] offset:384
	v_min_u32_e32 v26, 2, v20
	v_lshlrev_b32_e32 v26, 11, v26
	v_sub_u32_e32 v26, v14, v26
	global_load_dwordx4 v[68:71], v26, s[10:11] offset:384
	v_min_u32_e32 v26, 3, v20
	v_lshlrev_b32_e32 v26, 11, v26
	v_sub_u32_e32 v26, v14, v26
	global_load_dwordx4 v[72:75], v26, s[10:11] offset:384
	global_store_dwordx4 v0, v[92:95], s[12:13] offset:384
	global_store_dwordx4 v1, v[96:99], s[12:13] offset:384
	global_store_dwordx4 v2, v[100:103], s[12:13] offset:384
	v_mov_b32_e32 v0, v12
	v_mov_b32_e32 v6, v18
	v_mov_b32_e32 v1, v13
	v_mov_b32_e32 v7, v19
	v_mov_b32_e32 v2, v14
	v_mov_b32_e32 v8, v20
	s_waitcnt vmcnt(3)
	s_branch .Lpool_c1
.Lpool_c1_last:
	global_store_dwordx4 v0, v[92:95], s[12:13] offset:384
	global_store_dwordx4 v1, v[96:99], s[12:13] offset:384
	global_store_dwordx4 v2, v[100:103], s[12:13] offset:384
	s_mov_b32 s44, 0
	s_mov_b32 s46, 0x0
	v_add_u32_e32 v144, s46, v25
	v_lshrrev_b32_e32 v145, 6, v144
	v_mul_u32_u24_e32 v145, s47, v145
	v_lshrrev_b32_e32 v145, 17, v145
	v_mul_u32_u24_e32 v146, 0xc0, v145
	v_sub_u32_e32 v146, v144, v146
	v_lshrrev_b32_e32 v147, 3, v146
	v_mul_u32_u24_e32 v147, s47, v147
	v_lshrrev_b32_e32 v147, 17, v147
	v_mul_u32_u24_e32 v24, 24, v147
	v_sub_u32_e32 v24, v146, v24
	v_lshl_add_u32 v145, v145, 3, v147
	v_and_b32_e32 v6, 0x1fff, v145
	v_lshlrev_b32_e32 v145, 11, v145
	v_lshl_add_u32 v0, v24, 4, v145
	s_mov_b32 s46, 0x4000
	v_add_u32_e32 v144, s46, v25
	v_lshrrev_b32_e32 v145, 6, v144
	v_mul_u32_u24_e32 v145, s47, v145
	v_lshrrev_b32_e32 v145, 17, v145
	v_mul_u32_u24_e32 v146, 0xc0, v145
	v_sub_u32_e32 v146, v144, v146
	v_lshrrev_b32_e32 v147, 3, v146
	v_mul_u32_u24_e32 v147, s47, v147
	v_lshrrev_b32_e32 v147, 17, v147
	v_mul_u32_u24_e32 v24, 24, v147
	v_sub_u32_e32 v24, v146, v24
	v_lshl_add_u32 v145, v145, 3, v147
	v_and_b32_e32 v7, 0x1fff, v145
	v_lshlrev_b32_e32 v145, 11, v145
	v_lshl_add_u32 v1, v24, 4, v145
	global_load_dwordx4 v[28:31], v0, s[10:11] offset:768
	v_min_u32_e32 v26, 1, v6
	v_lshlrev_b32_e32 v26, 11, v26
	v_sub_u32_e32 v26, v0, v26
	global_load_dwordx4 v[32:35], v26, s[10:11] offset:768
	v_min_u32_e32 v26, 2, v6
	v_lshlrev_b32_e32 v26, 11, v26
	v_sub_u32_e32 v26, v0, v26
	global_load_dwordx4 v[36:39], v26, s[10:11] offset:768
	v_min_u32_e32 v26, 3, v6
	v_lshlrev_b32_e32 v26, 11, v26
	v_sub_u32_e32 v26, v0, v26
	global_load_dwordx4 v[40:43], v26, s[10:11] offset:768
	v_min_u32_e32 v26, 4, v6
	v_lshlrev_b32_e32 v26, 11, v26
	v_sub_u32_e32 v26, v0, v26
	global_load_dwordx4 v[44:47], v26, s[10:11] offset:768
	v_min_u32_e32 v26, 5, v6
	v_lshlrev_b32_e32 v26, 11, v26
	v_sub_u32_e32 v26, v0, v26
	global_load_dwordx4 v[48:51], v26, s[10:11] offset:768
	v_min_u32_e32 v26, 6, v6
	v_lshlrev_b32_e32 v26, 11, v26
	v_sub_u32_e32 v26, v0, v26
	global_load_dwordx4 v[52:55], v26, s[10:11] offset:768
	v_min_u32_e32 v26, 7, v6
	v_lshlrev_b32_e32 v26, 11, v26
	v_sub_u32_e32 v26, v0, v26
	global_load_dwordx4 v[56:59], v26, s[10:11] offset:768
	global_load_dwordx4 v[60:63], v1, s[10:11] offset:768
	v_min_u32_e32 v26, 1, v7
	v_lshlrev_b32_e32 v26, 11, v26
	v_sub_u32_e32 v26, v1, v26
	global_load_dwordx4 v[64:67], v26, s[10:11] offset:768
	v_min_u32_e32 v26, 2, v7
	v_lshlrev_b32_e32 v26, 11, v26
	v_sub_u32_e32 v26, v1, v26
	global_load_dwordx4 v[68:71], v26, s[10:11] offset:768
	v_min_u32_e32 v26, 3, v7
	v_lshlrev_b32_e32 v26, 11, v26
	v_sub_u32_e32 v26, v1, v26
	global_load_dwordx4 v[72:75], v26, s[10:11] offset:768
	v_min_u32_e32 v26, 4, v7
	v_lshlrev_b32_e32 v26, 11, v26
	v_sub_u32_e32 v26, v1, v26
	global_load_dwordx4 v[76:79], v26, s[10:11] offset:768
	v_min_u32_e32 v26, 5, v7
	v_lshlrev_b32_e32 v26, 11, v26
	v_sub_u32_e32 v26, v1, v26
	global_load_dwordx4 v[80:83], v26, s[10:11] offset:768
	v_min_u32_e32 v26, 6, v7
	v_lshlrev_b32_e32 v26, 11, v26
	v_sub_u32_e32 v26, v1, v26
	global_load_dwordx4 v[84:87], v26, s[10:11] offset:768
	v_min_u32_e32 v26, 7, v7
	v_lshlrev_b32_e32 v26, 11, v26
	v_sub_u32_e32 v26, v1, v26
	global_load_dwordx4 v[88:91], v26, s[10:11] offset:768
	s_waitcnt vmcnt(0)
.Lpool_c2:
	v_lshlrev_b32_e32 v116, 16, v28
	v_and_b32_e32 v117, 0xffff0000, v28
	v_lshlrev_b32_e32 v118, 16, v29
	v_and_b32_e32 v119, 0xffff0000, v29
	v_lshlrev_b32_e32 v120, 16, v30
	v_and_b32_e32 v121, 0xffff0000, v30
	v_lshlrev_b32_e32 v122, 16, v31
	v_and_b32_e32 v123, 0xffff0000, v31
	v_cmp_le_u32_e32 vcc, 1, v6
	v_cndmask_b32_e64 v140, 0, 1.0, vcc
	v_mov_b32_e32 v141, v140
	v_lshlrev_b32_e32 v132, 16, v32
	v_and_b32_e32 v133, 0xffff0000, v32
	v_lshlrev_b32_e32 v134, 16, v33
	v_and_b32_e32 v135, 0xffff0000, v33
	v_lshlrev_b32_e32 v136, 16, v34
	v_and_b32_e32 v137, 0xffff0000, v34
	v_lshlrev_b32_e32 v138, 16, v35
	v_and_b32_e32 v139, 0xffff0000, v35
	v_pk_fma_f32 v[124:125], v[132:133], v[140:141], v[116:117]
	v_pk_fma_f32 v[126:127], v[134:135], v[140:141], v[118:119]
	v_pk_fma_f32 v[128:129], v[136:137], v[140:141], v[120:121]
	v_pk_fma_f32 v[130:131], v[138:139], v[140:141], v[122:123]
	v_cmp_le_u32_e32 vcc, 2, v6
	v_cndmask_b32_e64 v140, 0, 1.0, vcc
	v_mov_b32_e32 v141, v140
	v_lshlrev_b32_e32 v132, 16, v36
	v_and_b32_e32 v133, 0xffff0000, v36
	v_lshlrev_b32_e32 v134, 16, v37
	v_and_b32_e32 v135, 0xffff0000, v37
	v_lshlrev_b32_e32 v136, 16, v38
	v_and_b32_e32 v137, 0xffff0000, v38
	v_lshlrev_b32_e32 v138, 16, v39
	v_and_b32_e32 v139, 0xffff0000, v39
	v_pk_fma_f32 v[124:125], v[132:133], v[140:141], v[124:125]
	v_pk_fma_f32 v[126:127], v[134:135], v[140:141], v[126:127]
	v_pk_fma_f32 v[128:129], v[136:137], v[140:141], v[128:129]
	v_pk_fma_f32 v[130:131], v[138:139], v[140:141], v[130:131]
	v_cmp_le_u32_e32 vcc, 3, v6
	v_cndmask_b32_e64 v140, 0, 1.0, vcc
	v_mov_b32_e32 v141, v140
	v_lshlrev_b32_e32 v132, 16, v40
	v_and_b32_e32 v133, 0xffff0000, v40
	v_lshlrev_b32_e32 v134, 16, v41
	v_and_b32_e32 v135, 0xffff0000, v41
	v_lshlrev_b32_e32 v136, 16, v42
	v_and_b32_e32 v137, 0xffff0000, v42
	v_lshlrev_b32_e32 v138, 16, v43
	v_and_b32_e32 v139, 0xffff0000, v43
	v_pk_fma_f32 v[124:125], v[132:133], v[140:141], v[124:125]
	v_pk_fma_f32 v[126:127], v[134:135], v[140:141], v[126:127]
	v_pk_fma_f32 v[128:129], v[136:137], v[140:141], v[128:129]
	v_pk_fma_f32 v[130:131], v[138:139], v[140:141], v[130:131]
	v_cmp_le_u32_e32 vcc, 4, v6
	v_cndmask_b32_e64 v140, 0, 1.0, vcc
	v_mov_b32_e32 v141, v140
	v_lshlrev_b32_e32 v132, 16, v44
	v_and_b32_e32 v133, 0xffff0000, v44
	v_lshlrev_b32_e32 v134, 16, v45
	v_and_b32_e32 v135, 0xffff0000, v45
	v_lshlrev_b32_e32 v136, 16, v46
	v_and_b32_e32 v137, 0xffff0000, v46
	v_lshlrev_b32_e32 v138, 16, v47
	v_and_b32_e32 v139, 0xffff0000, v47
	v_pk_fma_f32 v[124:125], v[132:133], v[140:141], v[124:125]
	v_pk_fma_f32 v[126:127], v[134:135], v[140:141], v[126:127]
	v_pk_fma_f32 v[128:129], v[136:137], v[140:141], v[128:129]
	v_pk_fma_f32 v[130:131], v[138:139], v[140:141], v[130:131]
	v_cmp_le_u32_e32 vcc, 5, v6
	v_cndmask_b32_e64 v140, 0, 1.0, vcc
	v_mov_b32_e32 v141, v140
	v_lshlrev_b32_e32 v132, 16, v48
	v_and_b32_e32 v133, 0xffff0000, v48
	v_lshlrev_b32_e32 v134, 16, v49
	v_and_b32_e32 v135, 0xffff0000, v49
	v_lshlrev_b32_e32 v136, 16, v50
	v_and_b32_e32 v137, 0xffff0000, v50
	v_lshlrev_b32_e32 v138, 16, v51
	v_and_b32_e32 v139, 0xffff0000, v51
	v_pk_fma_f32 v[124:125], v[132:133], v[140:141], v[124:125]
	v_pk_fma_f32 v[126:127], v[134:135], v[140:141], v[126:127]
	v_pk_fma_f32 v[128:129], v[136:137], v[140:141], v[128:129]
	v_pk_fma_f32 v[130:131], v[138:139], v[140:141], v[130:131]
	v_cmp_le_u32_e32 vcc, 6, v6
	v_cndmask_b32_e64 v140, 0, 1.0, vcc
	v_mov_b32_e32 v141, v140
	v_lshlrev_b32_e32 v132, 16, v52
	v_and_b32_e32 v133, 0xffff0000, v52
	v_lshlrev_b32_e32 v134, 16, v53
	v_and_b32_e32 v135, 0xffff0000, v53
	v_lshlrev_b32_e32 v136, 16, v54
	v_and_b32_e32 v137, 0xffff0000, v54
	v_lshlrev_b32_e32 v138, 16, v55
	v_and_b32_e32 v139, 0xffff0000, v55
	v_pk_fma_f32 v[124:125], v[132:133], v[140:141], v[124:125]
	v_pk_fma_f32 v[126:127], v[134:135], v[140:141], v[126:127]
	v_pk_fma_f32 v[128:129], v[136:137], v[140:141], v[128:129]
	v_pk_fma_f32 v[130:131], v[138:139], v[140:141], v[130:131]
	v_cmp_le_u32_e32 vcc, 7, v6
	v_cndmask_b32_e64 v140, 0, 1.0, vcc
	v_mov_b32_e32 v141, v140
	v_lshlrev_b32_e32 v132, 16, v56
	v_and_b32_e32 v133, 0xffff0000, v56
	v_lshlrev_b32_e32 v134, 16, v57
	v_and_b32_e32 v135, 0xffff0000, v57
	v_lshlrev_b32_e32 v136, 16, v58
	v_and_b32_e32 v137, 0xffff0000, v58
	v_lshlrev_b32_e32 v138, 16, v59
	v_and_b32_e32 v139, 0xffff0000, v59
	v_pk_fma_f32 v[124:125], v[132:133], v[140:141], v[124:125]
	v_pk_fma_f32 v[126:127], v[134:135], v[140:141], v[126:127]
	v_pk_fma_f32 v[128:129], v[136:137], v[140:141], v[128:129]
	v_pk_fma_f32 v[130:131], v[138:139], v[140:141], v[130:131]
	v_add_u32_e32 v144, 1, v6
	v_min_u32_e32 v144, 8, v144
	v_cvt_f32_u32_e32 v144, v144
	v_rcp_f32_e32 v142, v144
	s_nop 0
	v_fma_f32 v145, -v144, v142, 1.0
	v_fma_f32 v142, v145, v142, v142
	v_mov_b32_e32 v143, v142
	v_pk_fma_f32 v[132:133], v[124:125], v[142:143], v[116:117] neg_lo:[0,0,1] neg_hi:[0,0,1]
	v_pk_fma_f32 v[134:135], v[126:127], v[142:143], v[118:119] neg_lo:[0,0,1] neg_hi:[0,0,1]
	v_pk_fma_f32 v[136:137], v[128:129], v[142:143], v[120:121] neg_lo:[0,0,1] neg_hi:[0,0,1]
	v_pk_fma_f32 v[138:139], v[130:131], v[142:143], v[122:123] neg_lo:[0,0,1] neg_hi:[0,0,1]
	v_cvt_pk_bf16_f32 v92, v132, v133
	v_cvt_pk_bf16_f32 v93, v134, v135
	v_cvt_pk_bf16_f32 v94, v136, v137
	v_cvt_pk_bf16_f32 v95, v138, v139
	v_lshlrev_b32_e32 v116, 16, v60
	v_and_b32_e32 v117, 0xffff0000, v60
	v_lshlrev_b32_e32 v118, 16, v61
	v_and_b32_e32 v119, 0xffff0000, v61
	v_lshlrev_b32_e32 v120, 16, v62
	v_and_b32_e32 v121, 0xffff0000, v62
	v_lshlrev_b32_e32 v122, 16, v63
	v_and_b32_e32 v123, 0xffff0000, v63
	v_cmp_le_u32_e32 vcc, 1, v7
	v_cndmask_b32_e64 v140, 0, 1.0, vcc
	v_mov_b32_e32 v141, v140
	v_lshlrev_b32_e32 v132, 16, v64
	v_and_b32_e32 v133, 0xffff0000, v64
	v_lshlrev_b32_e32 v134, 16, v65
	v_and_b32_e32 v135, 0xffff0000, v65
	v_lshlrev_b32_e32 v136, 16, v66
	v_and_b32_e32 v137, 0xffff0000, v66
	v_lshlrev_b32_e32 v138, 16, v67
	v_and_b32_e32 v139, 0xffff0000, v67
	v_pk_fma_f32 v[124:125], v[132:133], v[140:141], v[116:117]
	v_pk_fma_f32 v[126:127], v[134:135], v[140:141], v[118:119]
	v_pk_fma_f32 v[128:129], v[136:137], v[140:141], v[120:121]
	v_pk_fma_f32 v[130:131], v[138:139], v[140:141], v[122:123]
	v_cmp_le_u32_e32 vcc, 2, v7
	v_cndmask_b32_e64 v140, 0, 1.0, vcc
	v_mov_b32_e32 v141, v140
	v_lshlrev_b32_e32 v132, 16, v68
	v_and_b32_e32 v133, 0xffff0000, v68
	v_lshlrev_b32_e32 v134, 16, v69
	v_and_b32_e32 v135, 0xffff0000, v69
	v_lshlrev_b32_e32 v136, 16, v70
	v_and_b32_e32 v137, 0xffff0000, v70
	v_lshlrev_b32_e32 v138, 16, v71
	v_and_b32_e32 v139, 0xffff0000, v71
	v_pk_fma_f32 v[124:125], v[132:133], v[140:141], v[124:125]
	v_pk_fma_f32 v[126:127], v[134:135], v[140:141], v[126:127]
	v_pk_fma_f32 v[128:129], v[136:137], v[140:141], v[128:129]
	v_pk_fma_f32 v[130:131], v[138:139], v[140:141], v[130:131]
	v_cmp_le_u32_e32 vcc, 3, v7
	v_cndmask_b32_e64 v140, 0, 1.0, vcc
	v_mov_b32_e32 v141, v140
	v_lshlrev_b32_e32 v132, 16, v72
	v_and_b32_e32 v133, 0xffff0000, v72
	v_lshlrev_b32_e32 v134, 16, v73
	v_and_b32_e32 v135, 0xffff0000, v73
	v_lshlrev_b32_e32 v136, 16, v74
	v_and_b32_e32 v137, 0xffff0000, v74
	v_lshlrev_b32_e32 v138, 16, v75
	v_and_b32_e32 v139, 0xffff0000, v75
	v_pk_fma_f32 v[124:125], v[132:133], v[140:141], v[124:125]
	v_pk_fma_f32 v[126:127], v[134:135], v[140:141], v[126:127]
	v_pk_fma_f32 v[128:129], v[136:137], v[140:141], v[128:129]
	v_pk_fma_f32 v[130:131], v[138:139], v[140:141], v[130:131]
	v_cmp_le_u32_e32 vcc, 4, v7
	v_cndmask_b32_e64 v140, 0, 1.0, vcc
	v_mov_b32_e32 v141, v140
	v_lshlrev_b32_e32 v132, 16, v76
	v_and_b32_e32 v133, 0xffff0000, v76
	v_lshlrev_b32_e32 v134, 16, v77
	v_and_b32_e32 v135, 0xffff0000, v77
	v_lshlrev_b32_e32 v136, 16, v78
	v_and_b32_e32 v137, 0xffff0000, v78
	v_lshlrev_b32_e32 v138, 16, v79
	v_and_b32_e32 v139, 0xffff0000, v79
	v_pk_fma_f32 v[124:125], v[132:133], v[140:141], v[124:125]
	v_pk_fma_f32 v[126:127], v[134:135], v[140:141], v[126:127]
	v_pk_fma_f32 v[128:129], v[136:137], v[140:141], v[128:129]
	v_pk_fma_f32 v[130:131], v[138:139], v[140:141], v[130:131]
	v_cmp_le_u32_e32 vcc, 5, v7
	v_cndmask_b32_e64 v140, 0, 1.0, vcc
	v_mov_b32_e32 v141, v140
	v_lshlrev_b32_e32 v132, 16, v80
	v_and_b32_e32 v133, 0xffff0000, v80
	v_lshlrev_b32_e32 v134, 16, v81
	v_and_b32_e32 v135, 0xffff0000, v81
	v_lshlrev_b32_e32 v136, 16, v82
	v_and_b32_e32 v137, 0xffff0000, v82
	v_lshlrev_b32_e32 v138, 16, v83
	v_and_b32_e32 v139, 0xffff0000, v83
	v_pk_fma_f32 v[124:125], v[132:133], v[140:141], v[124:125]
	v_pk_fma_f32 v[126:127], v[134:135], v[140:141], v[126:127]
	v_pk_fma_f32 v[128:129], v[136:137], v[140:141], v[128:129]
	v_pk_fma_f32 v[130:131], v[138:139], v[140:141], v[130:131]
	v_cmp_le_u32_e32 vcc, 6, v7
	v_cndmask_b32_e64 v140, 0, 1.0, vcc
	v_mov_b32_e32 v141, v140
	v_lshlrev_b32_e32 v132, 16, v84
	v_and_b32_e32 v133, 0xffff0000, v84
	v_lshlrev_b32_e32 v134, 16, v85
	v_and_b32_e32 v135, 0xffff0000, v85
	v_lshlrev_b32_e32 v136, 16, v86
	v_and_b32_e32 v137, 0xffff0000, v86
	v_lshlrev_b32_e32 v138, 16, v87
	v_and_b32_e32 v139, 0xffff0000, v87
	v_pk_fma_f32 v[124:125], v[132:133], v[140:141], v[124:125]
	v_pk_fma_f32 v[126:127], v[134:135], v[140:141], v[126:127]
	v_pk_fma_f32 v[128:129], v[136:137], v[140:141], v[128:129]
	v_pk_fma_f32 v[130:131], v[138:139], v[140:141], v[130:131]
	v_cmp_le_u32_e32 vcc, 7, v7
	v_cndmask_b32_e64 v140, 0, 1.0, vcc
	v_mov_b32_e32 v141, v140
	v_lshlrev_b32_e32 v132, 16, v88
	v_and_b32_e32 v133, 0xffff0000, v88
	v_lshlrev_b32_e32 v134, 16, v89
	v_and_b32_e32 v135, 0xffff0000, v89
	v_lshlrev_b32_e32 v136, 16, v90
	v_and_b32_e32 v137, 0xffff0000, v90
	v_lshlrev_b32_e32 v138, 16, v91
	v_and_b32_e32 v139, 0xffff0000, v91
	v_pk_fma_f32 v[124:125], v[132:133], v[140:141], v[124:125]
	v_pk_fma_f32 v[126:127], v[134:135], v[140:141], v[126:127]
	v_pk_fma_f32 v[128:129], v[136:137], v[140:141], v[128:129]
	v_pk_fma_f32 v[130:131], v[138:139], v[140:141], v[130:131]
	v_add_u32_e32 v144, 1, v7
	v_min_u32_e32 v144, 8, v144
	v_cvt_f32_u32_e32 v144, v144
	v_rcp_f32_e32 v142, v144
	s_nop 0
	v_fma_f32 v145, -v144, v142, 1.0
	v_fma_f32 v142, v145, v142, v142
	v_mov_b32_e32 v143, v142
	v_pk_fma_f32 v[132:133], v[124:125], v[142:143], v[116:117] neg_lo:[0,0,1] neg_hi:[0,0,1]
	v_pk_fma_f32 v[134:135], v[126:127], v[142:143], v[118:119] neg_lo:[0,0,1] neg_hi:[0,0,1]
	v_pk_fma_f32 v[136:137], v[128:129], v[142:143], v[120:121] neg_lo:[0,0,1] neg_hi:[0,0,1]
	v_pk_fma_f32 v[138:139], v[130:131], v[142:143], v[122:123] neg_lo:[0,0,1] neg_hi:[0,0,1]
	v_cvt_pk_bf16_f32 v96, v132, v133
	v_cvt_pk_bf16_f32 v97, v134, v135
	v_cvt_pk_bf16_f32 v98, v136, v137
	v_cvt_pk_bf16_f32 v99, v138, v139
	s_add_i32 s44, s44, 1
	s_cmp_lt_u32 s44, 3
	s_cbranch_scc0 .Lpool_c2_last
	s_mul_i32 s45, s44, 2
	s_add_i32 s46, s45, 0
	s_lshl_b32 s46, s46, 14
	v_add_u32_e32 v144, s46, v25
	v_lshrrev_b32_e32 v145, 6, v144
	v_mul_u32_u24_e32 v145, s47, v145
	v_lshrrev_b32_e32 v145, 17, v145
	v_mul_u32_u24_e32 v146, 0xc0, v145
	v_sub_u32_e32 v146, v144, v146
	v_lshrrev_b32_e32 v147, 3, v146
	v_mul_u32_u24_e32 v147, s47, v147
	v_lshrrev_b32_e32 v147, 17, v147
	v_mul_u32_u24_e32 v24, 24, v147
	v_sub_u32_e32 v24, v146, v24
	v_lshl_add_u32 v145, v145, 3, v147
	v_and_b32_e32 v18, 0x1fff, v145
	v_lshlrev_b32_e32 v145, 11, v145
	v_lshl_add_u32 v12, v24, 4, v145
	s_add_i32 s46, s45, 1
	s_lshl_b32 s46, s46, 14
	v_add_u32_e32 v144, s46, v25
	v_lshrrev_b32_e32 v145, 6, v144
	v_mul_u32_u24_e32 v145, s47, v145
	v_lshrrev_b32_e32 v145, 17, v145
	v_mul_u32_u24_e32 v146, 0xc0, v145
	v_sub_u32_e32 v146, v144, v146
	v_lshrrev_b32_e32 v147, 3, v146
	v_mul_u32_u24_e32 v147, s47, v147
	v_lshrrev_b32_e32 v147, 17, v147
	v_mul_u32_u24_e32 v24, 24, v147
	v_sub_u32_e32 v24, v146, v24
	v_lshl_add_u32 v145, v145, 3, v147
	v_and_b32_e32 v19, 0x1fff, v145
	v_lshlrev_b32_e32 v145, 11, v145
	v_lshl_add_u32 v13, v24, 4, v145
	global_load_dwordx4 v[28:31], v12, s[10:11] offset:768
	v_min_u32_e32 v26, 1, v18
	v_lshlrev_b32_e32 v26, 11, v26
	v_sub_u32_e32 v26, v12, v26
	global_load_dwordx4 v[32:35], v26, s[10:11] offset:768
	v_min_u32_e32 v26, 2, v18
	v_lshlrev_b32_e32 v26, 11, v26
	v_sub_u32_e32 v26, v12, v26
	global_load_dwordx4 v[36:39], v26, s[10:11] offset:768
	v_min_u32_e32 v26, 3, v18
	v_lshlrev_b32_e32 v26, 11, v26
	v_sub_u32_e32 v26, v12, v26
	global_load_dwordx4 v[40:43], v26, s[10:11] offset:768
	v_min_u32_e32 v26, 4, v18
	v_lshlrev_b32_e32 v26, 11, v26
	v_sub_u32_e32 v26, v12, v26
	global_load_dwordx4 v[44:47], v26, s[10:11] offset:768
	v_min_u32_e32 v26, 5, v18
	v_lshlrev_b32_e32 v26, 11, v26
	v_sub_u32_e32 v26, v12, v26
	global_load_dwordx4 v[48:51], v26, s[10:11] offset:768
	v_min_u32_e32 v26, 6, v18
	v_lshlrev_b32_e32 v26, 11, v26
	v_sub_u32_e32 v26, v12, v26
	global_load_dwordx4 v[52:55], v26, s[10:11] offset:768
	v_min_u32_e32 v26, 7, v18
	v_lshlrev_b32_e32 v26, 11, v26
	v_sub_u32_e32 v26, v12, v26
	global_load_dwordx4 v[56:59], v26, s[10:11] offset:768
	global_load_dwordx4 v[60:63], v13, s[10:11] offset:768
	v_min_u32_e32 v26, 1, v19
	v_lshlrev_b32_e32 v26, 11, v26
	v_sub_u32_e32 v26, v13, v26
	global_load_dwordx4 v[64:67], v26, s[10:11] offset:768
	v_min_u32_e32 v26, 2, v19
	v_lshlrev_b32_e32 v26, 11, v26
	v_sub_u32_e32 v26, v13, v26
	global_load_dwordx4 v[68:71], v26, s[10:11] offset:768
	v_min_u32_e32 v26, 3, v19
	v_lshlrev_b32_e32 v26, 11, v26
	v_sub_u32_e32 v26, v13, v26
	global_load_dwordx4 v[72:75], v26, s[10:11] offset:768
	v_min_u32_e32 v26, 4, v19
	v_lshlrev_b32_e32 v26, 11, v26
	v_sub_u32_e32 v26, v13, v26
	global_load_dwordx4 v[76:79], v26, s[10:11] offset:768
	v_min_u32_e32 v26, 5, v19
	v_lshlrev_b32_e32 v26, 11, v26
	v_sub_u32_e32 v26, v13, v26
	global_load_dwordx4 v[80:83], v26, s[10:11] offset:768
	v_min_u32_e32 v26, 6, v19
	v_lshlrev_b32_e32 v26, 11, v26
	v_sub_u32_e32 v26, v13, v26
	global_load_dwordx4 v[84:87], v26, s[10:11] offset:768
	v_min_u32_e32 v26, 7, v19
	v_lshlrev_b32_e32 v26, 11, v26
	v_sub_u32_e32 v26, v13, v26
	global_load_dwordx4 v[88:91], v26, s[10:11] offset:768
	global_store_dwordx4 v0, v[92:95], s[12:13] offset:768
	global_store_dwordx4 v1, v[96:99], s[12:13] offset:768
	v_mov_b32_e32 v0, v12
	v_mov_b32_e32 v6, v18
	v_mov_b32_e32 v1, v13
	v_mov_b32_e32 v7, v19
	s_waitcnt vmcnt(2)
	s_branch .Lpool_c2
.Lpool_c2_last:
	global_store_dwordx4 v0, v[92:95], s[12:13] offset:768
	global_store_dwordx4 v1, v[96:99], s[12:13] offset:768
	s_mov_b32 s44, 0
	s_mov_b32 s46, 0x0
	v_add_u32_e32 v144, s46, v25
	v_lshrrev_b32_e32 v145, 6, v144
	v_mul_u32_u24_e32 v145, s47, v145
	v_lshrrev_b32_e32 v145, 17, v145
	v_mul_u32_u24_e32 v146, 0xc0, v145
	v_sub_u32_e32 v146, v144, v146
	v_lshrrev_b32_e32 v147, 3, v146
	v_mul_u32_u24_e32 v147, s47, v147
	v_lshrrev_b32_e32 v147, 17, v147
	v_mul_u32_u24_e32 v24, 24, v147
	v_sub_u32_e32 v24, v146, v24
	v_lshl_add_u32 v145, v145, 3, v147
	v_and_b32_e32 v6, 0x1fff, v145
	v_lshlrev_b32_e32 v145, 11, v145
	v_lshl_add_u32 v0, v24, 4, v145
	global_load_dwordx4 v[28:31], v0, s[10:11] offset:1152
	v_min_u32_e32 v26, 1, v6
	v_lshlrev_b32_e32 v26, 11, v26
	v_sub_u32_e32 v26, v0, v26
	global_load_dwordx4 v[32:35], v26, s[10:11] offset:1152
	v_min_u32_e32 v26, 2, v6
	v_lshlrev_b32_e32 v26, 11, v26
	v_sub_u32_e32 v26, v0, v26
	global_load_dwordx4 v[36:39], v26, s[10:11] offset:1152
	v_min_u32_e32 v26, 3, v6
	v_lshlrev_b32_e32 v26, 11, v26
	v_sub_u32_e32 v26, v0, v26
	global_load_dwordx4 v[40:43], v26, s[10:11] offset:1152
	v_min_u32_e32 v26, 4, v6
	v_lshlrev_b32_e32 v26, 11, v26
	v_sub_u32_e32 v26, v0, v26
	global_load_dwordx4 v[44:47], v26, s[10:11] offset:1152
	v_min_u32_e32 v26, 5, v6
	v_lshlrev_b32_e32 v26, 11, v26
	v_sub_u32_e32 v26, v0, v26
	global_load_dwordx4 v[48:51], v26, s[10:11] offset:1152
	v_min_u32_e32 v26, 6, v6
	v_lshlrev_b32_e32 v26, 11, v26
	v_sub_u32_e32 v26, v0, v26
	global_load_dwordx4 v[52:55], v26, s[10:11] offset:1152
	v_min_u32_e32 v26, 7, v6
	v_lshlrev_b32_e32 v26, 11, v26
	v_sub_u32_e32 v26, v0, v26
	global_load_dwordx4 v[56:59], v26, s[10:11] offset:1152
	v_min_u32_e32 v26, 8, v6
	v_lshlrev_b32_e32 v26, 11, v26
	v_sub_u32_e32 v26, v0, v26
	global_load_dwordx4 v[60:63], v26, s[10:11] offset:1152
	v_min_u32_e32 v26, 9, v6
	v_lshlrev_b32_e32 v26, 11, v26
	v_sub_u32_e32 v26, v0, v26
	global_load_dwordx4 v[64:67], v26, s[10:11] offset:1152
	v_min_u32_e32 v26, 10, v6
	v_lshlrev_b32_e32 v26, 11, v26
	v_sub_u32_e32 v26, v0, v26
	global_load_dwordx4 v[68:71], v26, s[10:11] offset:1152
	v_min_u32_e32 v26, 11, v6
	v_lshlrev_b32_e32 v26, 11, v26
	v_sub_u32_e32 v26, v0, v26
	global_load_dwordx4 v[72:75], v26, s[10:11] offset:1152
	v_min_u32_e32 v26, 12, v6
	v_lshlrev_b32_e32 v26, 11, v26
	v_sub_u32_e32 v26, v0, v26
	global_load_dwordx4 v[76:79], v26, s[10:11] offset:1152
	v_min_u32_e32 v26, 13, v6
	v_lshlrev_b32_e32 v26, 11, v26
	v_sub_u32_e32 v26, v0, v26
	global_load_dwordx4 v[80:83], v26, s[10:11] offset:1152
	v_min_u32_e32 v26, 14, v6
	v_lshlrev_b32_e32 v26, 11, v26
	v_sub_u32_e32 v26, v0, v26
	global_load_dwordx4 v[84:87], v26, s[10:11] offset:1152
	v_min_u32_e32 v26, 15, v6
	v_lshlrev_b32_e32 v26, 11, v26
	v_sub_u32_e32 v26, v0, v26
	global_load_dwordx4 v[88:91], v26, s[10:11] offset:1152
	s_waitcnt vmcnt(0)
.Lpool_c3:
	v_lshlrev_b32_e32 v116, 16, v28
	v_and_b32_e32 v117, 0xffff0000, v28
	v_lshlrev_b32_e32 v118, 16, v29
	v_and_b32_e32 v119, 0xffff0000, v29
	v_lshlrev_b32_e32 v120, 16, v30
	v_and_b32_e32 v121, 0xffff0000, v30
	v_lshlrev_b32_e32 v122, 16, v31
	v_and_b32_e32 v123, 0xffff0000, v31
	v_cmp_le_u32_e32 vcc, 1, v6
	v_cndmask_b32_e64 v140, 0, 1.0, vcc
	v_mov_b32_e32 v141, v140
	v_lshlrev_b32_e32 v132, 16, v32
	v_and_b32_e32 v133, 0xffff0000, v32
	v_lshlrev_b32_e32 v134, 16, v33
	v_and_b32_e32 v135, 0xffff0000, v33
	v_lshlrev_b32_e32 v136, 16, v34
	v_and_b32_e32 v137, 0xffff0000, v34
	v_lshlrev_b32_e32 v138, 16, v35
	v_and_b32_e32 v139, 0xffff0000, v35
	v_pk_fma_f32 v[124:125], v[132:133], v[140:141], v[116:117]
	v_pk_fma_f32 v[126:127], v[134:135], v[140:141], v[118:119]
	v_pk_fma_f32 v[128:129], v[136:137], v[140:141], v[120:121]
	v_pk_fma_f32 v[130:131], v[138:139], v[140:141], v[122:123]
	v_cmp_le_u32_e32 vcc, 2, v6
	v_cndmask_b32_e64 v140, 0, 1.0, vcc
	v_mov_b32_e32 v141, v140
	v_lshlrev_b32_e32 v132, 16, v36
	v_and_b32_e32 v133, 0xffff0000, v36
	v_lshlrev_b32_e32 v134, 16, v37
	v_and_b32_e32 v135, 0xffff0000, v37
	v_lshlrev_b32_e32 v136, 16, v38
	v_and_b32_e32 v137, 0xffff0000, v38
	v_lshlrev_b32_e32 v138, 16, v39
	v_and_b32_e32 v139, 0xffff0000, v39
	v_pk_fma_f32 v[124:125], v[132:133], v[140:141], v[124:125]
	v_pk_fma_f32 v[126:127], v[134:135], v[140:141], v[126:127]
	v_pk_fma_f32 v[128:129], v[136:137], v[140:141], v[128:129]
	v_pk_fma_f32 v[130:131], v[138:139], v[140:141], v[130:131]
	v_cmp_le_u32_e32 vcc, 3, v6
	v_cndmask_b32_e64 v140, 0, 1.0, vcc
	v_mov_b32_e32 v141, v140
	v_lshlrev_b32_e32 v132, 16, v40
	v_and_b32_e32 v133, 0xffff0000, v40
	v_lshlrev_b32_e32 v134, 16, v41
	v_and_b32_e32 v135, 0xffff0000, v41
	v_lshlrev_b32_e32 v136, 16, v42
	v_and_b32_e32 v137, 0xffff0000, v42
	v_lshlrev_b32_e32 v138, 16, v43
	v_and_b32_e32 v139, 0xffff0000, v43
	v_pk_fma_f32 v[124:125], v[132:133], v[140:141], v[124:125]
	v_pk_fma_f32 v[126:127], v[134:135], v[140:141], v[126:127]
	v_pk_fma_f32 v[128:129], v[136:137], v[140:141], v[128:129]
	v_pk_fma_f32 v[130:131], v[138:139], v[140:141], v[130:131]
	v_cmp_le_u32_e32 vcc, 4, v6
	v_cndmask_b32_e64 v140, 0, 1.0, vcc
	v_mov_b32_e32 v141, v140
	v_lshlrev_b32_e32 v132, 16, v44
	v_and_b32_e32 v133, 0xffff0000, v44
	v_lshlrev_b32_e32 v134, 16, v45
	v_and_b32_e32 v135, 0xffff0000, v45
	v_lshlrev_b32_e32 v136, 16, v46
	v_and_b32_e32 v137, 0xffff0000, v46
	v_lshlrev_b32_e32 v138, 16, v47
	v_and_b32_e32 v139, 0xffff0000, v47
	v_pk_fma_f32 v[124:125], v[132:133], v[140:141], v[124:125]
	v_pk_fma_f32 v[126:127], v[134:135], v[140:141], v[126:127]
	v_pk_fma_f32 v[128:129], v[136:137], v[140:141], v[128:129]
	v_pk_fma_f32 v[130:131], v[138:139], v[140:141], v[130:131]
	v_cmp_le_u32_e32 vcc, 5, v6
	v_cndmask_b32_e64 v140, 0, 1.0, vcc
	v_mov_b32_e32 v141, v140
	v_lshlrev_b32_e32 v132, 16, v48
	v_and_b32_e32 v133, 0xffff0000, v48
	v_lshlrev_b32_e32 v134, 16, v49
	v_and_b32_e32 v135, 0xffff0000, v49
	v_lshlrev_b32_e32 v136, 16, v50
	v_and_b32_e32 v137, 0xffff0000, v50
	v_lshlrev_b32_e32 v138, 16, v51
	v_and_b32_e32 v139, 0xffff0000, v51
	v_pk_fma_f32 v[124:125], v[132:133], v[140:141], v[124:125]
	v_pk_fma_f32 v[126:127], v[134:135], v[140:141], v[126:127]
	v_pk_fma_f32 v[128:129], v[136:137], v[140:141], v[128:129]
	v_pk_fma_f32 v[130:131], v[138:139], v[140:141], v[130:131]
	v_cmp_le_u32_e32 vcc, 6, v6
	v_cndmask_b32_e64 v140, 0, 1.0, vcc
	v_mov_b32_e32 v141, v140
	v_lshlrev_b32_e32 v132, 16, v52
	v_and_b32_e32 v133, 0xffff0000, v52
	v_lshlrev_b32_e32 v134, 16, v53
	v_and_b32_e32 v135, 0xffff0000, v53
	v_lshlrev_b32_e32 v136, 16, v54
	v_and_b32_e32 v137, 0xffff0000, v54
	v_lshlrev_b32_e32 v138, 16, v55
	v_and_b32_e32 v139, 0xffff0000, v55
	v_pk_fma_f32 v[124:125], v[132:133], v[140:141], v[124:125]
	v_pk_fma_f32 v[126:127], v[134:135], v[140:141], v[126:127]
	v_pk_fma_f32 v[128:129], v[136:137], v[140:141], v[128:129]
	v_pk_fma_f32 v[130:131], v[138:139], v[140:141], v[130:131]
	v_cmp_le_u32_e32 vcc, 7, v6
	v_cndmask_b32_e64 v140, 0, 1.0, vcc
	v_mov_b32_e32 v141, v140
	v_lshlrev_b32_e32 v132, 16, v56
	v_and_b32_e32 v133, 0xffff0000, v56
	v_lshlrev_b32_e32 v134, 16, v57
	v_and_b32_e32 v135, 0xffff0000, v57
	v_lshlrev_b32_e32 v136, 16, v58
	v_and_b32_e32 v137, 0xffff0000, v58
	v_lshlrev_b32_e32 v138, 16, v59
	v_and_b32_e32 v139, 0xffff0000, v59
	v_pk_fma_f32 v[124:125], v[132:133], v[140:141], v[124:125]
	v_pk_fma_f32 v[126:127], v[134:135], v[140:141], v[126:127]
	v_pk_fma_f32 v[128:129], v[136:137], v[140:141], v[128:129]
	v_pk_fma_f32 v[130:131], v[138:139], v[140:141], v[130:131]
	v_cmp_le_u32_e32 vcc, 8, v6
	v_cndmask_b32_e64 v140, 0, 1.0, vcc
	v_mov_b32_e32 v141, v140
	v_lshlrev_b32_e32 v132, 16, v60
	v_and_b32_e32 v133, 0xffff0000, v60
	v_lshlrev_b32_e32 v134, 16, v61
	v_and_b32_e32 v135, 0xffff0000, v61
	v_lshlrev_b32_e32 v136, 16, v62
	v_and_b32_e32 v137, 0xffff0000, v62
	v_lshlrev_b32_e32 v138, 16, v63
	v_and_b32_e32 v139, 0xffff0000, v63
	v_pk_fma_f32 v[124:125], v[132:133], v[140:141], v[124:125]
	v_pk_fma_f32 v[126:127], v[134:135], v[140:141], v[126:127]
	v_pk_fma_f32 v[128:129], v[136:137], v[140:141], v[128:129]
	v_pk_fma_f32 v[130:131], v[138:139], v[140:141], v[130:131]
	v_cmp_le_u32_e32 vcc, 9, v6
	v_cndmask_b32_e64 v140, 0, 1.0, vcc
	v_mov_b32_e32 v141, v140
	v_lshlrev_b32_e32 v132, 16, v64
	v_and_b32_e32 v133, 0xffff0000, v64
	v_lshlrev_b32_e32 v134, 16, v65
	v_and_b32_e32 v135, 0xffff0000, v65
	v_lshlrev_b32_e32 v136, 16, v66
	v_and_b32_e32 v137, 0xffff0000, v66
	v_lshlrev_b32_e32 v138, 16, v67
	v_and_b32_e32 v139, 0xffff0000, v67
	v_pk_fma_f32 v[124:125], v[132:133], v[140:141], v[124:125]
	v_pk_fma_f32 v[126:127], v[134:135], v[140:141], v[126:127]
	v_pk_fma_f32 v[128:129], v[136:137], v[140:141], v[128:129]
	v_pk_fma_f32 v[130:131], v[138:139], v[140:141], v[130:131]
	v_cmp_le_u32_e32 vcc, 10, v6
	v_cndmask_b32_e64 v140, 0, 1.0, vcc
	v_mov_b32_e32 v141, v140
	v_lshlrev_b32_e32 v132, 16, v68
	v_and_b32_e32 v133, 0xffff0000, v68
	v_lshlrev_b32_e32 v134, 16, v69
	v_and_b32_e32 v135, 0xffff0000, v69
	v_lshlrev_b32_e32 v136, 16, v70
	v_and_b32_e32 v137, 0xffff0000, v70
	v_lshlrev_b32_e32 v138, 16, v71
	v_and_b32_e32 v139, 0xffff0000, v71
	v_pk_fma_f32 v[124:125], v[132:133], v[140:141], v[124:125]
	v_pk_fma_f32 v[126:127], v[134:135], v[140:141], v[126:127]
	v_pk_fma_f32 v[128:129], v[136:137], v[140:141], v[128:129]
	v_pk_fma_f32 v[130:131], v[138:139], v[140:141], v[130:131]
	v_cmp_le_u32_e32 vcc, 11, v6
	v_cndmask_b32_e64 v140, 0, 1.0, vcc
	v_mov_b32_e32 v141, v140
	v_lshlrev_b32_e32 v132, 16, v72
	v_and_b32_e32 v133, 0xffff0000, v72
	v_lshlrev_b32_e32 v134, 16, v73
	v_and_b32_e32 v135, 0xffff0000, v73
	v_lshlrev_b32_e32 v136, 16, v74
	v_and_b32_e32 v137, 0xffff0000, v74
	v_lshlrev_b32_e32 v138, 16, v75
	v_and_b32_e32 v139, 0xffff0000, v75
	v_pk_fma_f32 v[124:125], v[132:133], v[140:141], v[124:125]
	v_pk_fma_f32 v[126:127], v[134:135], v[140:141], v[126:127]
	v_pk_fma_f32 v[128:129], v[136:137], v[140:141], v[128:129]
	v_pk_fma_f32 v[130:131], v[138:139], v[140:141], v[130:131]
	v_cmp_le_u32_e32 vcc, 12, v6
	v_cndmask_b32_e64 v140, 0, 1.0, vcc
	v_mov_b32_e32 v141, v140
	v_lshlrev_b32_e32 v132, 16, v76
	v_and_b32_e32 v133, 0xffff0000, v76
	v_lshlrev_b32_e32 v134, 16, v77
	v_and_b32_e32 v135, 0xffff0000, v77
	v_lshlrev_b32_e32 v136, 16, v78
	v_and_b32_e32 v137, 0xffff0000, v78
	v_lshlrev_b32_e32 v138, 16, v79
	v_and_b32_e32 v139, 0xffff0000, v79
	v_pk_fma_f32 v[124:125], v[132:133], v[140:141], v[124:125]
	v_pk_fma_f32 v[126:127], v[134:135], v[140:141], v[126:127]
	v_pk_fma_f32 v[128:129], v[136:137], v[140:141], v[128:129]
	v_pk_fma_f32 v[130:131], v[138:139], v[140:141], v[130:131]
	v_cmp_le_u32_e32 vcc, 13, v6
	v_cndmask_b32_e64 v140, 0, 1.0, vcc
	v_mov_b32_e32 v141, v140
	v_lshlrev_b32_e32 v132, 16, v80
	v_and_b32_e32 v133, 0xffff0000, v80
	v_lshlrev_b32_e32 v134, 16, v81
	v_and_b32_e32 v135, 0xffff0000, v81
	v_lshlrev_b32_e32 v136, 16, v82
	v_and_b32_e32 v137, 0xffff0000, v82
	v_lshlrev_b32_e32 v138, 16, v83
	v_and_b32_e32 v139, 0xffff0000, v83
	v_pk_fma_f32 v[124:125], v[132:133], v[140:141], v[124:125]
	v_pk_fma_f32 v[126:127], v[134:135], v[140:141], v[126:127]
	v_pk_fma_f32 v[128:129], v[136:137], v[140:141], v[128:129]
	v_pk_fma_f32 v[130:131], v[138:139], v[140:141], v[130:131]
	v_cmp_le_u32_e32 vcc, 14, v6
	v_cndmask_b32_e64 v140, 0, 1.0, vcc
	v_mov_b32_e32 v141, v140
	v_lshlrev_b32_e32 v132, 16, v84
	v_and_b32_e32 v133, 0xffff0000, v84
	v_lshlrev_b32_e32 v134, 16, v85
	v_and_b32_e32 v135, 0xffff0000, v85
	v_lshlrev_b32_e32 v136, 16, v86
	v_and_b32_e32 v137, 0xffff0000, v86
	v_lshlrev_b32_e32 v138, 16, v87
	v_and_b32_e32 v139, 0xffff0000, v87
	v_pk_fma_f32 v[124:125], v[132:133], v[140:141], v[124:125]
	v_pk_fma_f32 v[126:127], v[134:135], v[140:141], v[126:127]
	v_pk_fma_f32 v[128:129], v[136:137], v[140:141], v[128:129]
	v_pk_fma_f32 v[130:131], v[138:139], v[140:141], v[130:131]
	v_cmp_le_u32_e32 vcc, 15, v6
	v_cndmask_b32_e64 v140, 0, 1.0, vcc
	v_mov_b32_e32 v141, v140
	v_lshlrev_b32_e32 v132, 16, v88
	v_and_b32_e32 v133, 0xffff0000, v88
	v_lshlrev_b32_e32 v134, 16, v89
	v_and_b32_e32 v135, 0xffff0000, v89
	v_lshlrev_b32_e32 v136, 16, v90
	v_and_b32_e32 v137, 0xffff0000, v90
	v_lshlrev_b32_e32 v138, 16, v91
	v_and_b32_e32 v139, 0xffff0000, v91
	v_pk_fma_f32 v[124:125], v[132:133], v[140:141], v[124:125]
	v_pk_fma_f32 v[126:127], v[134:135], v[140:141], v[126:127]
	v_pk_fma_f32 v[128:129], v[136:137], v[140:141], v[128:129]
	v_pk_fma_f32 v[130:131], v[138:139], v[140:141], v[130:131]
	v_add_u32_e32 v144, 1, v6
	v_min_u32_e32 v144, 16, v144
	v_cvt_f32_u32_e32 v144, v144
	v_rcp_f32_e32 v142, v144
	s_nop 0
	v_fma_f32 v145, -v144, v142, 1.0
	v_fma_f32 v142, v145, v142, v142
	v_mov_b32_e32 v143, v142
	v_pk_fma_f32 v[132:133], v[124:125], v[142:143], v[116:117] neg_lo:[0,0,1] neg_hi:[0,0,1]
	v_pk_fma_f32 v[134:135], v[126:127], v[142:143], v[118:119] neg_lo:[0,0,1] neg_hi:[0,0,1]
	v_pk_fma_f32 v[136:137], v[128:129], v[142:143], v[120:121] neg_lo:[0,0,1] neg_hi:[0,0,1]
	v_pk_fma_f32 v[138:139], v[130:131], v[142:143], v[122:123] neg_lo:[0,0,1] neg_hi:[0,0,1]
	v_cvt_pk_bf16_f32 v92, v132, v133
	v_cvt_pk_bf16_f32 v93, v134, v135
	v_cvt_pk_bf16_f32 v94, v136, v137
	v_cvt_pk_bf16_f32 v95, v138, v139
	s_add_i32 s44, s44, 1
	s_cmp_lt_u32 s44, 6
	s_cbranch_scc0 .Lpool_c3_last
	s_mul_i32 s45, s44, 1
	s_add_i32 s46, s45, 0
	s_lshl_b32 s46, s46, 14
	v_add_u32_e32 v144, s46, v25
	v_lshrrev_b32_e32 v145, 6, v144
	v_mul_u32_u24_e32 v145, s47, v145
	v_lshrrev_b32_e32 v145, 17, v145
	v_mul_u32_u24_e32 v146, 0xc0, v145
	v_sub_u32_e32 v146, v144, v146
	v_lshrrev_b32_e32 v147, 3, v146
	v_mul_u32_u24_e32 v147, s47, v147
	v_lshrrev_b32_e32 v147, 17, v147
	v_mul_u32_u24_e32 v24, 24, v147
	v_sub_u32_e32 v24, v146, v24
	v_lshl_add_u32 v145, v145, 3, v147
	v_and_b32_e32 v18, 0x1fff, v145
	v_lshlrev_b32_e32 v145, 11, v145
	v_lshl_add_u32 v12, v24, 4, v145
	global_load_dwordx4 v[28:31], v12, s[10:11] offset:1152
	v_min_u32_e32 v26, 1, v18
	v_lshlrev_b32_e32 v26, 11, v26
	v_sub_u32_e32 v26, v12, v26
	global_load_dwordx4 v[32:35], v26, s[10:11] offset:1152
	v_min_u32_e32 v26, 2, v18
	v_lshlrev_b32_e32 v26, 11, v26
	v_sub_u32_e32 v26, v12, v26
	global_load_dwordx4 v[36:39], v26, s[10:11] offset:1152
	v_min_u32_e32 v26, 3, v18
	v_lshlrev_b32_e32 v26, 11, v26
	v_sub_u32_e32 v26, v12, v26
	global_load_dwordx4 v[40:43], v26, s[10:11] offset:1152
	v_min_u32_e32 v26, 4, v18
	v_lshlrev_b32_e32 v26, 11, v26
	v_sub_u32_e32 v26, v12, v26
	global_load_dwordx4 v[44:47], v26, s[10:11] offset:1152
	v_min_u32_e32 v26, 5, v18
	v_lshlrev_b32_e32 v26, 11, v26
	v_sub_u32_e32 v26, v12, v26
	global_load_dwordx4 v[48:51], v26, s[10:11] offset:1152
	v_min_u32_e32 v26, 6, v18
	v_lshlrev_b32_e32 v26, 11, v26
	v_sub_u32_e32 v26, v12, v26
	global_load_dwordx4 v[52:55], v26, s[10:11] offset:1152
	v_min_u32_e32 v26, 7, v18
	v_lshlrev_b32_e32 v26, 11, v26
	v_sub_u32_e32 v26, v12, v26
	global_load_dwordx4 v[56:59], v26, s[10:11] offset:1152
	v_min_u32_e32 v26, 8, v18
	v_lshlrev_b32_e32 v26, 11, v26
	v_sub_u32_e32 v26, v12, v26
	global_load_dwordx4 v[60:63], v26, s[10:11] offset:1152
	v_min_u32_e32 v26, 9, v18
	v_lshlrev_b32_e32 v26, 11, v26
	v_sub_u32_e32 v26, v12, v26
	global_load_dwordx4 v[64:67], v26, s[10:11] offset:1152
	v_min_u32_e32 v26, 10, v18
	v_lshlrev_b32_e32 v26, 11, v26
	v_sub_u32_e32 v26, v12, v26
	global_load_dwordx4 v[68:71], v26, s[10:11] offset:1152
	v_min_u32_e32 v26, 11, v18
	v_lshlrev_b32_e32 v26, 11, v26
	v_sub_u32_e32 v26, v12, v26
	global_load_dwordx4 v[72:75], v26, s[10:11] offset:1152
	v_min_u32_e32 v26, 12, v18
	v_lshlrev_b32_e32 v26, 11, v26
	v_sub_u32_e32 v26, v12, v26
	global_load_dwordx4 v[76:79], v26, s[10:11] offset:1152
	v_min_u32_e32 v26, 13, v18
	v_lshlrev_b32_e32 v26, 11, v26
	v_sub_u32_e32 v26, v12, v26
	global_load_dwordx4 v[80:83], v26, s[10:11] offset:1152
	v_min_u32_e32 v26, 14, v18
	v_lshlrev_b32_e32 v26, 11, v26
	v_sub_u32_e32 v26, v12, v26
	global_load_dwordx4 v[84:87], v26, s[10:11] offset:1152
	v_min_u32_e32 v26, 15, v18
	v_lshlrev_b32_e32 v26, 11, v26
	v_sub_u32_e32 v26, v12, v26
	global_load_dwordx4 v[88:91], v26, s[10:11] offset:1152
	global_store_dwordx4 v0, v[92:95], s[12:13] offset:1152
	v_mov_b32_e32 v0, v12
	v_mov_b32_e32 v6, v18
	s_waitcnt vmcnt(1)
	s_branch .Lpool_c3
.Lpool_c3_last:
	global_store_dwordx4 v0, v[92:95], s[12:13] offset:1152
	v_mov_b32_e32 v76, v241
	s_branch .LBB0_292
